# attention: K/V global prefetch loads and their address VALU moved from between QK and PV into the first PV MFMA gaps (first ds_write waits vmcnt(0)), on top of v25
# speedup vs baseline: 1.0078x; 1.0078x over previous
; #define SBAR() __builtin_amdgcn_sched_barrier(0)
; __device__ __forceinline__ void finishSM(f32x16& p0, f32x16& p1, float alpha, float& l_reg, bf16x8& pa0, bf16x8& pa1, bf16x8& pa2, bf16x8& pa3) {
;   for (int r = 0; r < 16; ++r) p1[r] = __builtin_amdgcn_exp2f(p1[r]);
;   float ps = 0; for (int r = 0; r < 16; ++r) ps += p0[r]; for (int r = 0; r < 16; ++r) ps += p1[r];
;   { auto rr = __builtin_amdgcn_permlane32_swap(__float_as_uint(ps), __float_as_uint(ps), false, false);
;     ps = __uint_as_float(rr[0]) + __uint_as_float(rr[1]); }
;   l_reg = l_reg * alpha + ps;
;     ...
;   PK4(p0, 0, pa0); PK4(p0, 8, pa1); PK4(p1, 0, pa2); PK4(p1, 8, pa3);
;     ...
; }
; template <int D0, int BOFF> __device__ __forceinline__ void pv_one_i(f32x16& od, int vb, bf16x8 pa0, bf16x8 pa1, bf16x8 pa2, bf16x8 pa3) {
;   const s16x4 l0 = tr_read<BOFF + v_rd_off(D0, 0, 0)>(vb), h0 = tr_read<BOFF + v_rd_off(D0, 0, 1)>(vb), l1 = tr_read<BOFF + v_rd_off(D0, 1, 0)>(vb), h1 = tr_read<BOFF + v_rd_off(D0, 1, 1)>(vb);
;   const s16x4 l2 = tr_read<BOFF + v_rd_off(D0, 2, 0)>(vb), h2 = tr_read<BOFF + v_rd_off(D0, 2, 1)>(vb), l3 = tr_read<BOFF + v_rd_off(D0, 3, 0)>(vb), h3 = tr_read<BOFF + v_rd_off(D0, 3, 1)>(vb);
;   asm volatile("s_waitcnt lgkmcnt(0)" ::: "memory"); SBAR();
;     ...
;   od = __builtin_amdgcn_mfma_f32_32x32x16_bf16(pa0, PK(l0, h0), od, 0, 0, 0);
;   od = __builtin_amdgcn_mfma_f32_32x32x16_bf16(pa1, PK(l1, h1), od, 0, 0, 0);
;   od = __builtin_amdgcn_mfma_f32_32x32x16_bf16(pa2, PK(l2, h2), od, 0, 0, 0);
;   od = __builtin_amdgcn_mfma_f32_32x32x16_bf16(pa3, PK(l3, h3), od, 0, 0, 0);
;     ...
; }
; template <int BOFF> __device__ __forceinline__ void pv_i(f32x16* o, int vb, bf16x8 pa0, bf16x8 pa1, bf16x8 pa2, bf16x8 pa3) {
;   pv_one_i<0, BOFF>(o[0], vb, pa0, pa1, pa2, pa3); pv_one_i<1, BOFF>(o[1], vb, pa0, pa1, pa2, pa3); pv_one_i<2, BOFF>(o[2], vb, pa0, pa1, pa2, pa3); pv_one_i<3, BOFF>(o[3], vb, pa0, pa1, pa2, pa3);
; }
.LBB0_352:
	s_waitcnt lgkmcnt(0)
	s_barrier
	ds_read_b128 v[80:83], v207 offset:16384
	ds_read_b128 v[84:87], v207 offset:24576
	ds_read_b128 v[162:165], v208 offset:16384
	ds_read_b128 v[166:169], v208 offset:24576
	v_exp_f32_e32 v170, v72
	v_exp_f32_e32 v171, v73
	v_exp_f32_e32 v172, v74
	v_exp_f32_e32 v173, v75
	v_exp_f32_e32 v174, v76
	v_exp_f32_e32 v175, v77
	v_exp_f32_e32 v176, v78
	v_exp_f32_e32 v79, v79
	s_waitcnt lgkmcnt(3)
	v_mfma_f32_32x32x16_bf16 v[96:111], v[80:83], v[142:145], 0
	v_exp_f32_e32 v236, v64
	v_add_f32_e32 v64, 0, v229
	v_add_f32_e32 v64, v243, v64
	v_add_f32_e32 v64, v244, v64
	s_waitcnt lgkmcnt(2)
	v_mfma_f32_32x32x16_bf16 v[80:95], v[84:87], v[142:145], 0
	v_add_f32_e32 v64, v246, v64
	v_add_f32_e32 v64, v242, v64
	v_add_f32_e32 v64, v245, v64
	s_waitcnt lgkmcnt(1)
	v_mfma_f32_32x32x16_bf16 v[96:111], v[162:165], v[138:141], v[96:111]
	v_add_f32_e32 v64, v227, v64
	v_add_f32_e32 v64, v228, v64
	v_add_f32_e32 v64, v223, v64
	s_waitcnt lgkmcnt(0)
	v_mfma_f32_32x32x16_bf16 v[80:95], v[166:169], v[138:141], v[80:95]
	ds_read_b128 v[162:165], v209 offset:16384
	ds_read_b128 v[166:169], v209 offset:24576
	v_add_f32_e32 v64, v226, v64
	v_add_f32_e32 v64, v224, v64
	v_add_f32_e32 v64, v225, v64
	v_add_f32_e32 v64, v220, v64
	v_exp_f32_e32 v237, v65
	s_waitcnt lgkmcnt(1)
	v_mfma_f32_32x32x16_bf16 v[96:111], v[162:165], v[112:115], v[96:111]
	v_add_f32_e32 v64, v222, v64
	v_exp_f32_e32 v238, v66
	v_add_f32_e32 v64, v219, v64
	v_exp_f32_e32 v239, v67
	s_waitcnt lgkmcnt(0)
	v_mfma_f32_32x32x16_bf16 v[80:95], v[166:169], v[112:115], v[80:95]
	ds_read_b128 v[162:165], v210 offset:16384
	ds_read_b128 v[166:169], v210 offset:24576
	v_add_f32_e32 v64, v221, v64
	v_exp_f32_e32 v247, v68
	v_add_f32_e32 v64, v236, v64
	v_exp_f32_e32 v248, v69
	s_waitcnt lgkmcnt(1)
	v_mfma_f32_32x32x16_bf16 v[96:111], v[162:165], v[116:119], v[96:111]
	v_add_f32_e32 v64, v237, v64
	v_exp_f32_e32 v249, v70
	v_add_f32_e32 v64, v238, v64
	v_exp_f32_e32 v252, v71
	s_waitcnt lgkmcnt(0)
	v_mfma_f32_32x32x16_bf16 v[80:95], v[166:169], v[116:119], v[80:95]
	ds_read_b128 v[162:165], v190 offset:16384
	ds_read_b128 v[166:169], v190 offset:24576
	v_add_f32_e32 v64, v239, v64
	v_add_f32_e32 v64, v247, v64
	v_add_f32_e32 v64, v248, v64
	v_add_f32_e32 v64, v249, v64
	v_add_f32_e32 v64, v252, v64
	v_add_f32_e32 v64, v170, v64
	s_waitcnt lgkmcnt(1)
	v_mfma_f32_32x32x16_bf16 v[96:111], v[162:165], v[120:123], v[96:111]
	v_add_f32_e32 v64, v171, v64
	v_add_f32_e32 v64, v172, v64
	v_add_f32_e32 v64, v173, v64
	v_add_f32_e32 v64, v174, v64
	v_add_f32_e32 v64, v175, v64
	s_waitcnt lgkmcnt(0)
	v_mfma_f32_32x32x16_bf16 v[80:95], v[166:169], v[120:123], v[80:95]
	ds_read_b128 v[162:165], v191 offset:16384
	ds_read_b128 v[166:169], v191 offset:24576
	v_add_f32_e32 v64, v176, v64
	v_add_f32_e32 v64, v79, v64
	v_mov_b32_e32 v65, v64
	s_nop 1
	v_permlane32_swap_b32_e32 v64, v65
	v_add_f32_e32 v64, v64, v65
	s_waitcnt lgkmcnt(1)
	v_mfma_f32_32x32x16_bf16 v[96:111], v[162:165], v[124:127], v[96:111]
	v_add_f32_e32 v128, v215, v64
	v_cvt_pk_bf16_f32 v64, v229, v243
	v_cvt_pk_bf16_f32 v65, v244, v246
	v_cvt_pk_bf16_f32 v66, v242, v245
	v_cvt_pk_bf16_f32 v67, v227, v228
	s_waitcnt lgkmcnt(0)
	v_mfma_f32_32x32x16_bf16 v[80:95], v[166:169], v[124:127], v[80:95]
	ds_read_b128 v[162:165], v192 offset:16384
	ds_read_b128 v[166:169], v192 offset:24576
	v_cvt_pk_bf16_f32 v68, v223, v226
	v_cvt_pk_bf16_f32 v69, v224, v225
	v_cvt_pk_bf16_f32 v70, v220, v222
	v_cvt_pk_bf16_f32 v71, v219, v221
	v_cvt_pk_bf16_f32 v72, v236, v237
	v_cvt_pk_bf16_f32 v73, v238, v239
	s_waitcnt lgkmcnt(1)
	v_mfma_f32_32x32x16_bf16 v[96:111], v[162:165], v[130:133], v[96:111]
	v_cvt_pk_bf16_f32 v74, v247, v248
	v_cvt_pk_bf16_f32 v75, v249, v252
	v_cvt_pk_bf16_f32 v76, v170, v171
	v_cvt_pk_bf16_f32 v77, v172, v173
	v_cvt_pk_bf16_f32 v78, v174, v175
	s_waitcnt lgkmcnt(0)
	v_mfma_f32_32x32x16_bf16 v[80:95], v[166:169], v[130:133], v[80:95]
	ds_read_b128 v[162:165], v193 offset:16384
	ds_read_b128 v[166:169], v193 offset:24576
	ds_read_b64_tr_b16 v[180:181], v206 offset:0
	ds_read_b64_tr_b16 v[182:183], v206 offset:0x800
	ds_read_b64_tr_b16 v[184:185], v206 offset:0x1000
	ds_read_b64_tr_b16 v[186:187], v206 offset:0x1800
	ds_read_b64_tr_b16 v[216:217], v206 offset:0x2000
	ds_read_b64_tr_b16 v[218:219], v206 offset:0x2800
	ds_read_b64_tr_b16 v[220:221], v206 offset:0x3000
	ds_read_b64_tr_b16 v[222:223], v206 offset:0x3800
	v_cvt_pk_bf16_f32 v79, v176, v79
	s_nop 0
	v_permlane32_swap_b32_e32 v64, v66
	v_permlane32_swap_b32_e32 v65, v67
	v_permlane32_swap_b32_e32 v68, v70
	v_permlane32_swap_b32_e32 v69, v71
	s_waitcnt lgkmcnt(9)
	v_mfma_f32_32x32x16_bf16 v[96:111], v[162:165], v[134:137], v[96:111]
	v_permlane32_swap_b32_e32 v72, v74
	v_permlane32_swap_b32_e32 v73, v75
	v_permlane32_swap_b32_e32 v76, v78
	v_permlane32_swap_b32_e32 v77, v79
	s_waitcnt lgkmcnt(8)
	v_mfma_f32_32x32x16_bf16 v[80:95], v[166:169], v[134:137], v[80:95]
	s_waitcnt vmcnt(0)
	ds_write_b128 v211, v[146:149] offset:32768
	s_nop 0
	s_waitcnt lgkmcnt(7)
	v_mfma_f32_32x32x16_bf16 v[0:15], v[64:67], v[180:183], v[0:15]
	ds_read_b64_tr_b16 v[180:181], v206 offset:0x200
	ds_read_b64_tr_b16 v[182:183], v206 offset:0xa00
	v_add_co_u32_e32 v166, vcc, s19, v178
	s_nop 1
	v_addc_co_u32_e32 v167, vcc, -1, v179, vcc
	v_add_co_u32_e32 v170, vcc, s20, v178
	s_nop 1
	v_addc_co_u32_e32 v171, vcc, -1, v179, vcc
	s_waitcnt lgkmcnt(7)
	v_mfma_f32_32x32x16_bf16 v[0:15], v[68:71], v[184:187], v[0:15]
	ds_read_b64_tr_b16 v[184:185], v206 offset:0x1200
	ds_read_b64_tr_b16 v[186:187], v206 offset:0x1a00
	global_load_dwordx4 v[162:165], v[166:167], off
	s_nop 0
	global_load_dwordx4 v[166:169], v[166:167], off offset:-512
	s_nop 0
	global_load_dwordx4 v[174:177], v[170:171], off
	s_nop 0
	global_load_dwordx4 v[170:173], v[170:171], off offset:-512
	s_waitcnt lgkmcnt(7)
; #define SBAR() __builtin_amdgcn_sched_barrier(0)
; template <int D0, int BOFF> __device__ __forceinline__ void pv_one_i(f32x16& od, int vb, bf16x8 pa0, bf16x8 pa1, bf16x8 pa2, bf16x8 pa3) {
;   const s16x4 l0 = tr_read<BOFF + v_rd_off(D0, 0, 0)>(vb), h0 = tr_read<BOFF + v_rd_off(D0, 0, 1)>(vb), l1 = tr_read<BOFF + v_rd_off(D0, 1, 0)>(vb), h1 = tr_read<BOFF + v_rd_off(D0, 1, 1)>(vb);
;   const s16x4 l2 = tr_read<BOFF + v_rd_off(D0, 2, 0)>(vb), h2 = tr_read<BOFF + v_rd_off(D0, 2, 1)>(vb), l3 = tr_read<BOFF + v_rd_off(D0, 3, 0)>(vb), h3 = tr_read<BOFF + v_rd_off(D0, 3, 1)>(vb);
;   asm volatile("s_waitcnt lgkmcnt(0)" ::: "memory"); SBAR();
;     ...
;   od = __builtin_amdgcn_mfma_f32_32x32x16_bf16(pa0, PK(l0, h0), od, 0, 0, 0);
;   od = __builtin_amdgcn_mfma_f32_32x32x16_bf16(pa1, PK(l1, h1), od, 0, 0, 0);
;   od = __builtin_amdgcn_mfma_f32_32x32x16_bf16(pa2, PK(l2, h2), od, 0, 0, 0);
;   od = __builtin_amdgcn_mfma_f32_32x32x16_bf16(pa3, PK(l3, h3), od, 0, 0, 0);
;     ...
; }
; template <int BOFF> __device__ __forceinline__ void pv_i(f32x16* o, int vb, bf16x8 pa0, bf16x8 pa1, bf16x8 pa2, bf16x8 pa3) {
;   pv_one_i<0, BOFF>(o[0], vb, pa0, pa1, pa2, pa3); pv_one_i<1, BOFF>(o[1], vb, pa0, pa1, pa2, pa3); pv_one_i<2, BOFF>(o[2], vb, pa0, pa1, pa2, pa3); pv_one_i<3, BOFF>(o[3], vb, pa0, pa1, pa2, pa3);
; }
	v_mfma_f32_32x32x16_bf16 v[0:15], v[72:75], v[216:219], v[0:15]
	ds_read_b64_tr_b16 v[216:217], v206 offset:0x2200
	ds_read_b64_tr_b16 v[218:219], v206 offset:0x2a00
	s_waitcnt lgkmcnt(7)
	v_mfma_f32_32x32x16_bf16 v[0:15], v[76:79], v[220:223], v[0:15]
	ds_read_b64_tr_b16 v[220:221], v206 offset:0x3200
	ds_read_b64_tr_b16 v[222:223], v206 offset:0x3a00
	ds_write_b128 v212, v[150:153] offset:32768
	s_waitcnt lgkmcnt(7)
	v_mfma_f32_32x32x16_bf16 v[16:31], v[64:67], v[180:183], v[16:31]
	ds_read_b64_tr_b16 v[180:181], v206 offset:0x400
	ds_read_b64_tr_b16 v[182:183], v206 offset:0xc00
	s_waitcnt lgkmcnt(7)
	v_mfma_f32_32x32x16_bf16 v[16:31], v[68:71], v[184:187], v[16:31]
	ds_read_b64_tr_b16 v[184:185], v206 offset:0x1400
	ds_read_b64_tr_b16 v[186:187], v206 offset:0x1c00
	s_waitcnt lgkmcnt(7)
	v_mfma_f32_32x32x16_bf16 v[16:31], v[72:75], v[216:219], v[16:31]
	ds_read_b64_tr_b16 v[216:217], v206 offset:0x2400
	ds_read_b64_tr_b16 v[218:219], v206 offset:0x2c00
	s_waitcnt lgkmcnt(7)
	v_mfma_f32_32x32x16_bf16 v[16:31], v[76:79], v[220:223], v[16:31]
	ds_read_b64_tr_b16 v[220:221], v206 offset:0x3400
	ds_read_b64_tr_b16 v[222:223], v206 offset:0x3c00
	ds_write_b128 v213, v[154:157] offset:32768
	s_waitcnt lgkmcnt(7)
	v_mfma_f32_32x32x16_bf16 v[32:47], v[64:67], v[180:183], v[32:47]
	ds_read_b64_tr_b16 v[180:181], v206 offset:0x600
	ds_read_b64_tr_b16 v[182:183], v206 offset:0xe00
	s_waitcnt lgkmcnt(7)
	v_mfma_f32_32x32x16_bf16 v[32:47], v[68:71], v[184:187], v[32:47]
	ds_read_b64_tr_b16 v[184:185], v206 offset:0x1600
	ds_read_b64_tr_b16 v[186:187], v206 offset:0x1e00
	s_waitcnt lgkmcnt(7)
	v_mfma_f32_32x32x16_bf16 v[32:47], v[72:75], v[216:219], v[32:47]
	ds_read_b64_tr_b16 v[216:217], v206 offset:0x2600
	ds_read_b64_tr_b16 v[218:219], v206 offset:0x2e00
	s_waitcnt lgkmcnt(7)
	v_mfma_f32_32x32x16_bf16 v[32:47], v[76:79], v[220:223], v[32:47]
	ds_read_b64_tr_b16 v[220:221], v206 offset:0x3600
	ds_read_b64_tr_b16 v[222:223], v206 offset:0x3e00
	ds_write_b128 v214, v[158:161] offset:32768
	s_waitcnt lgkmcnt(7)
	v_mfma_f32_32x32x16_bf16 v[48:63], v[64:67], v[180:183], v[48:63]
	v_exp_f32_e32 v215, v108
	s_waitcnt vmcnt(4)
	v_exp_f32_e32 v181, v96
	v_exp_f32_e32 v183, v97
	v_exp_f32_e32 v188, v102
	v_exp_f32_e32 v189, v103
	v_exp_f32_e32 v196, v104
	s_waitcnt lgkmcnt(5)
	v_mfma_f32_32x32x16_bf16 v[48:63], v[68:71], v[184:187], v[48:63]
	v_exp_f32_e32 v184, v98
	v_exp_f32_e32 v185, v99
	v_exp_f32_e32 v186, v100
	v_exp_f32_e32 v187, v101
	v_exp_f32_e32 v197, v105
	v_exp_f32_e32 v198, v106
	v_exp_f32_e32 v199, v107
	s_waitcnt lgkmcnt(3)
	v_mfma_f32_32x32x16_bf16 v[48:63], v[72:75], v[216:219], v[48:63]
	v_exp_f32_e32 v216, v109
	v_exp_f32_e32 v217, v110
	v_exp_f32_e32 v218, v111
	s_waitcnt lgkmcnt(0)
	s_barrier
	v_mfma_f32_32x32x16_bf16 v[48:63], v[76:79], v[220:223], v[48:63]
	ds_read_b128 v[64:67], v207 offset:32768
	ds_read_b128 v[96:99], v207 offset:40960
	ds_read_b128 v[146:149], v208 offset:32768
	ds_read_b128 v[150:153], v208 offset:40960
	v_exp_f32_e32 v154, v88
	v_exp_f32_e32 v155, v89
	v_exp_f32_e32 v156, v90
	v_exp_f32_e32 v157, v91
	v_exp_f32_e32 v158, v92
	v_exp_f32_e32 v159, v93
	v_exp_f32_e32 v160, v94
	v_exp_f32_e32 v95, v95
	s_waitcnt lgkmcnt(3)
	v_mfma_f32_32x32x16_bf16 v[64:79], v[64:67], v[142:145], 0
	v_exp_f32_e32 v236, v80
	v_add_f32_e32 v80, 0, v181
	v_add_f32_e32 v80, v183, v80
	v_add_f32_e32 v80, v184, v80
	s_waitcnt lgkmcnt(2)
	v_mfma_f32_32x32x16_bf16 v[96:111], v[96:99], v[142:145], 0
	v_add_f32_e32 v80, v185, v80
	v_add_f32_e32 v80, v186, v80
	v_add_f32_e32 v80, v187, v80
	s_waitcnt lgkmcnt(1)
	v_mfma_f32_32x32x16_bf16 v[64:79], v[146:149], v[138:141], v[64:79]
	v_add_f32_e32 v80, v188, v80
	v_add_f32_e32 v80, v189, v80
	v_add_f32_e32 v80, v196, v80
	s_waitcnt lgkmcnt(0)
	v_mfma_f32_32x32x16_bf16 v[96:111], v[150:153], v[138:141], v[96:111]
	ds_read_b128 v[146:149], v209 offset:32768
	ds_read_b128 v[150:153], v209 offset:40960
	v_add_f32_e32 v80, v197, v80
	v_add_f32_e32 v80, v198, v80
	v_add_f32_e32 v80, v199, v80
	v_add_f32_e32 v80, v215, v80
	v_exp_f32_e32 v237, v81
	s_waitcnt lgkmcnt(1)
	v_mfma_f32_32x32x16_bf16 v[64:79], v[146:149], v[112:115], v[64:79]
	v_add_f32_e32 v80, v216, v80
	v_exp_f32_e32 v238, v82
	v_add_f32_e32 v80, v217, v80
	v_exp_f32_e32 v239, v83
	s_waitcnt lgkmcnt(0)
	v_mfma_f32_32x32x16_bf16 v[96:111], v[150:153], v[112:115], v[96:111]
	ds_read_b128 v[146:149], v210 offset:32768
	ds_read_b128 v[150:153], v210 offset:40960
	v_add_f32_e32 v80, v218, v80
	v_exp_f32_e32 v247, v84
	v_add_f32_e32 v80, v236, v80
	v_exp_f32_e32 v248, v85
	s_waitcnt lgkmcnt(1)
	v_mfma_f32_32x32x16_bf16 v[64:79], v[146:149], v[116:119], v[64:79]
	v_add_f32_e32 v80, v237, v80
	v_exp_f32_e32 v249, v86
	v_add_f32_e32 v80, v238, v80
	v_exp_f32_e32 v252, v87
	s_waitcnt lgkmcnt(0)
	v_mfma_f32_32x32x16_bf16 v[96:111], v[150:153], v[116:119], v[96:111]
	ds_read_b128 v[146:149], v190 offset:32768
	ds_read_b128 v[150:153], v190 offset:40960
	v_add_f32_e32 v80, v239, v80
	v_add_f32_e32 v80, v247, v80
	v_add_f32_e32 v80, v248, v80
	v_add_f32_e32 v80, v249, v80
	v_add_f32_e32 v80, v252, v80
	v_add_f32_e32 v80, v154, v80
	s_waitcnt lgkmcnt(1)
	v_mfma_f32_32x32x16_bf16 v[64:79], v[146:149], v[120:123], v[64:79]
	v_add_f32_e32 v80, v155, v80
	v_add_f32_e32 v80, v156, v80
	v_add_f32_e32 v80, v157, v80
	v_add_f32_e32 v80, v158, v80
	v_add_f32_e32 v80, v159, v80
	s_waitcnt lgkmcnt(0)
	v_mfma_f32_32x32x16_bf16 v[96:111], v[150:153], v[120:123], v[96:111]
	ds_read_b128 v[146:149], v191 offset:32768
	ds_read_b128 v[150:153], v191 offset:40960
	v_add_f32_e32 v80, v160, v80
	v_add_f32_e32 v180, v95, v80
	v_mov_b32_e32 v182, v180
	v_cvt_pk_bf16_f32 v80, v181, v183
	v_cvt_pk_bf16_f32 v81, v184, v185
	v_cvt_pk_bf16_f32 v82, v186, v187
	s_waitcnt lgkmcnt(1)
; #define SBAR() __builtin_amdgcn_sched_barrier(0)
; template <int D0, int BOFF> __device__ __forceinline__ void pv_one_i(f32x16& od, int vb, bf16x8 pa0, bf16x8 pa1, bf16x8 pa2, bf16x8 pa3) {
;   const s16x4 l0 = tr_read<BOFF + v_rd_off(D0, 0, 0)>(vb), h0 = tr_read<BOFF + v_rd_off(D0, 0, 1)>(vb), l1 = tr_read<BOFF + v_rd_off(D0, 1, 0)>(vb), h1 = tr_read<BOFF + v_rd_off(D0, 1, 1)>(vb);
;   const s16x4 l2 = tr_read<BOFF + v_rd_off(D0, 2, 0)>(vb), h2 = tr_read<BOFF + v_rd_off(D0, 2, 1)>(vb), l3 = tr_read<BOFF + v_rd_off(D0, 3, 0)>(vb), h3 = tr_read<BOFF + v_rd_off(D0, 3, 1)>(vb);
;   asm volatile("s_waitcnt lgkmcnt(0)" ::: "memory"); SBAR();
;     ...
;   od = __builtin_amdgcn_mfma_f32_32x32x16_bf16(pa0, PK(l0, h0), od, 0, 0, 0);
;   od = __builtin_amdgcn_mfma_f32_32x32x16_bf16(pa1, PK(l1, h1), od, 0, 0, 0);
;   od = __builtin_amdgcn_mfma_f32_32x32x16_bf16(pa2, PK(l2, h2), od, 0, 0, 0);
;   od = __builtin_amdgcn_mfma_f32_32x32x16_bf16(pa3, PK(l3, h3), od, 0, 0, 0);
;     ...
; }
; template <int BOFF> __device__ __forceinline__ void pv_i(f32x16* o, int vb, bf16x8 pa0, bf16x8 pa1, bf16x8 pa2, bf16x8 pa3) {
;   pv_one_i<0, BOFF>(o[0], vb, pa0, pa1, pa2, pa3); pv_one_i<1, BOFF>(o[1], vb, pa0, pa1, pa2, pa3); pv_one_i<2, BOFF>(o[2], vb, pa0, pa1, pa2, pa3); pv_one_i<3, BOFF>(o[3], vb, pa0, pa1, pa2, pa3);
; }
	v_mfma_f32_32x32x16_bf16 v[64:79], v[146:149], v[124:127], v[64:79]
	v_cvt_pk_bf16_f32 v83, v188, v189
	v_cvt_pk_bf16_f32 v84, v196, v197
	v_cvt_pk_bf16_f32 v85, v198, v199
	v_cvt_pk_bf16_f32 v86, v215, v216
	v_cvt_pk_bf16_f32 v87, v217, v218
	s_waitcnt lgkmcnt(0)
	v_mfma_f32_32x32x16_bf16 v[96:111], v[150:153], v[124:127], v[96:111]
	ds_read_b128 v[146:149], v192 offset:32768
	ds_read_b128 v[150:153], v192 offset:40960
	v_cvt_pk_bf16_f32 v88, v236, v237
	v_cvt_pk_bf16_f32 v89, v238, v239
	v_cvt_pk_bf16_f32 v90, v247, v248
	v_cvt_pk_bf16_f32 v91, v249, v252
	v_cvt_pk_bf16_f32 v92, v154, v155
	v_cvt_pk_bf16_f32 v93, v156, v157
	s_waitcnt lgkmcnt(1)
	v_mfma_f32_32x32x16_bf16 v[64:79], v[146:149], v[130:133], v[64:79]
	v_cvt_pk_bf16_f32 v94, v158, v159
	v_cvt_pk_bf16_f32 v95, v160, v95
	s_nop 1
	v_permlane32_swap_b32_e32 v180, v182
	v_permlane32_swap_b32_e32 v80, v82
	s_waitcnt lgkmcnt(0)
	v_mfma_f32_32x32x16_bf16 v[96:111], v[150:153], v[130:133], v[96:111]
	ds_read_b128 v[146:149], v193 offset:32768
	ds_read_b128 v[150:153], v193 offset:40960
	ds_read_b64_tr_b16 v[184:185], v206 offset:0x4000
	ds_read_b64_tr_b16 v[186:187], v206 offset:0x4800
	ds_read_b64_tr_b16 v[216:217], v206 offset:0x5000
	ds_read_b64_tr_b16 v[218:219], v206 offset:0x5800
	ds_read_b64_tr_b16 v[220:221], v206 offset:0x6000
	ds_read_b64_tr_b16 v[222:223], v206 offset:0x6800
	ds_read_b64_tr_b16 v[224:225], v206 offset:0x7000
	ds_read_b64_tr_b16 v[226:227], v206 offset:0x7800
	v_permlane32_swap_b32_e32 v81, v83
	v_permlane32_swap_b32_e32 v84, v86
	v_permlane32_swap_b32_e32 v85, v87
	v_permlane32_swap_b32_e32 v88, v90
	v_permlane32_swap_b32_e32 v89, v91
	v_permlane32_swap_b32_e32 v92, v94
	s_waitcnt lgkmcnt(9)
	v_mfma_f32_32x32x16_bf16 v[64:79], v[146:149], v[134:137], v[64:79]
	v_permlane32_swap_b32_e32 v93, v95
	s_waitcnt lgkmcnt(8)
	v_mfma_f32_32x32x16_bf16 v[96:111], v[150:153], v[134:137], v[96:111]
	s_waitcnt vmcnt(0)
	ds_write_b128 v211, v[162:165]
	s_nop 0
	s_waitcnt lgkmcnt(7)
	v_mfma_f32_32x32x16_bf16 v[0:15], v[80:83], v[184:187], v[0:15]
	ds_read_b64_tr_b16 v[184:185], v206 offset:0x4200
	ds_read_b64_tr_b16 v[186:187], v206 offset:0x4a00
	v_add_co_u32_e32 v150, vcc, s21, v178
	s_nop 1
	v_addc_co_u32_e32 v151, vcc, -1, v179, vcc
	v_add_co_u32_e32 v154, vcc, s22, v178
	s_nop 1
	v_addc_co_u32_e32 v155, vcc, -1, v179, vcc
	s_waitcnt lgkmcnt(7)
	v_mfma_f32_32x32x16_bf16 v[0:15], v[84:87], v[216:219], v[0:15]
	ds_read_b64_tr_b16 v[216:217], v206 offset:0x5200
	ds_read_b64_tr_b16 v[218:219], v206 offset:0x5a00
	global_load_dwordx4 v[146:149], v[150:151], off
	s_nop 0
	global_load_dwordx4 v[150:153], v[150:151], off offset:-512
	s_nop 0
	global_load_dwordx4 v[158:161], v[154:155], off
	s_nop 0
	global_load_dwordx4 v[154:157], v[154:155], off offset:-512
	s_waitcnt lgkmcnt(7)
	v_mfma_f32_32x32x16_bf16 v[0:15], v[88:91], v[220:223], v[0:15]
	ds_read_b64_tr_b16 v[220:221], v206 offset:0x6200
	ds_read_b64_tr_b16 v[222:223], v206 offset:0x6a00
	s_waitcnt lgkmcnt(7)
	v_mfma_f32_32x32x16_bf16 v[0:15], v[92:95], v[224:227], v[0:15]
	ds_read_b64_tr_b16 v[224:225], v206 offset:0x7200
	ds_read_b64_tr_b16 v[226:227], v206 offset:0x7a00
	ds_write_b128 v212, v[174:177]
	s_waitcnt lgkmcnt(7)
	v_mfma_f32_32x32x16_bf16 v[16:31], v[80:83], v[184:187], v[16:31]
	ds_read_b64_tr_b16 v[184:185], v206 offset:0x4400
	ds_read_b64_tr_b16 v[186:187], v206 offset:0x4c00
	s_waitcnt lgkmcnt(7)
	v_mfma_f32_32x32x16_bf16 v[16:31], v[84:87], v[216:219], v[16:31]
	ds_read_b64_tr_b16 v[216:217], v206 offset:0x5400
	ds_read_b64_tr_b16 v[218:219], v206 offset:0x5c00
	s_waitcnt lgkmcnt(7)
	v_mfma_f32_32x32x16_bf16 v[16:31], v[88:91], v[220:223], v[16:31]
	ds_read_b64_tr_b16 v[220:221], v206 offset:0x6400
	ds_read_b64_tr_b16 v[222:223], v206 offset:0x6c00
	s_waitcnt lgkmcnt(7)
	v_mfma_f32_32x32x16_bf16 v[16:31], v[92:95], v[224:227], v[16:31]
	ds_read_b64_tr_b16 v[224:225], v206 offset:0x7400
	ds_read_b64_tr_b16 v[226:227], v206 offset:0x7c00
	ds_write_b128 v213, v[166:169]
	s_waitcnt lgkmcnt(7)
	v_mfma_f32_32x32x16_bf16 v[32:47], v[80:83], v[184:187], v[32:47]
	ds_read_b64_tr_b16 v[184:185], v206 offset:0x4600
	ds_read_b64_tr_b16 v[186:187], v206 offset:0x4e00
	s_waitcnt lgkmcnt(7)
	v_mfma_f32_32x32x16_bf16 v[32:47], v[84:87], v[216:219], v[32:47]
	ds_read_b64_tr_b16 v[216:217], v206 offset:0x5600
	ds_read_b64_tr_b16 v[218:219], v206 offset:0x5e00
	s_waitcnt lgkmcnt(7)
	v_mfma_f32_32x32x16_bf16 v[32:47], v[88:91], v[220:223], v[32:47]
	ds_read_b64_tr_b16 v[220:221], v206 offset:0x6600
	ds_read_b64_tr_b16 v[222:223], v206 offset:0x6e00
	s_waitcnt lgkmcnt(7)
	v_mfma_f32_32x32x16_bf16 v[32:47], v[92:95], v[224:227], v[32:47]
	ds_read_b64_tr_b16 v[224:225], v206 offset:0x7600
	ds_read_b64_tr_b16 v[226:227], v206 offset:0x7e00
	ds_write_b128 v214, v[170:173]
	s_waitcnt lgkmcnt(7)
	v_mfma_f32_32x32x16_bf16 v[48:63], v[80:83], v[184:187], v[48:63]
	v_exp_f32_e32 v215, v74
	s_waitcnt vmcnt(4)
	v_exp_f32_e32 v184, v64
	v_exp_f32_e32 v185, v65
	v_exp_f32_e32 v186, v66
	v_exp_f32_e32 v187, v67
	v_exp_f32_e32 v188, v68
	s_waitcnt lgkmcnt(5)
	v_mfma_f32_32x32x16_bf16 v[48:63], v[84:87], v[216:219], v[48:63]
	v_exp_f32_e32 v219, v78
	v_exp_f32_e32 v189, v69
	v_exp_f32_e32 v196, v70
	v_exp_f32_e32 v197, v71
	v_exp_f32_e32 v198, v72
	v_exp_f32_e32 v199, v73
	v_exp_f32_e32 v216, v75
	s_waitcnt lgkmcnt(3)
	v_mfma_f32_32x32x16_bf16 v[48:63], v[88:91], v[220:223], v[48:63]
	v_exp_f32_e32 v220, v79
	v_exp_f32_e32 v217, v76
	v_exp_f32_e32 v218, v77
	s_waitcnt lgkmcnt(0)
	s_barrier
; #define SBAR() __builtin_amdgcn_sched_barrier(0)
; template <int BOFF> __device__ __forceinline__ void qkt_i(f32x16& p0, f32x16& p1, const int (&kb)[4], const bf16x8* qr) {
;   p0 = f32x16{}; p1 = f32x16{};
; #pragma unroll
;   for (int d0 = 0; d0 < 8; ++d0) { const int off = BOFF + (d0 >> 2) * 128;
;     const bf16x8 b0 = LDSV(kb[d0 & 3] + off), b1 = LDSV(kb[d0 & 3] + off + 8192);
;     p0 = __builtin_amdgcn_mfma_f32_32x32x16_bf16(b0, qr[d0], p0, 0, 0, 0);
;     p1 = __builtin_amdgcn_mfma_f32_32x32x16_bf16(b1, qr[d0], p1, 0, 0, 0); }
; }
; template <int D0, int BOFF> __device__ __forceinline__ void pv_one_i(f32x16& od, int vb, bf16x8 pa0, bf16x8 pa1, bf16x8 pa2, bf16x8 pa3) {
;   const s16x4 l0 = tr_read<BOFF + v_rd_off(D0, 0, 0)>(vb), h0 = tr_read<BOFF + v_rd_off(D0, 0, 1)>(vb), l1 = tr_read<BOFF + v_rd_off(D0, 1, 0)>(vb), h1 = tr_read<BOFF + v_rd_off(D0, 1, 1)>(vb);
;   const s16x4 l2 = tr_read<BOFF + v_rd_off(D0, 2, 0)>(vb), h2 = tr_read<BOFF + v_rd_off(D0, 2, 1)>(vb), l3 = tr_read<BOFF + v_rd_off(D0, 3, 0)>(vb), h3 = tr_read<BOFF + v_rd_off(D0, 3, 1)>(vb);
;   asm volatile("s_waitcnt lgkmcnt(0)" ::: "memory"); SBAR();
;     ...
;   od = __builtin_amdgcn_mfma_f32_32x32x16_bf16(pa0, PK(l0, h0), od, 0, 0, 0);
;   od = __builtin_amdgcn_mfma_f32_32x32x16_bf16(pa1, PK(l1, h1), od, 0, 0, 0);
;   od = __builtin_amdgcn_mfma_f32_32x32x16_bf16(pa2, PK(l2, h2), od, 0, 0, 0);
;   od = __builtin_amdgcn_mfma_f32_32x32x16_bf16(pa3, PK(l3, h3), od, 0, 0, 0);
;     ...
; }
; template <int BOFF> __device__ __forceinline__ void pv_i(f32x16* o, int vb, bf16x8 pa0, bf16x8 pa1, bf16x8 pa2, bf16x8 pa3) {
;   pv_one_i<0, BOFF>(o[0], vb, pa0, pa1, pa2, pa3); pv_one_i<1, BOFF>(o[1], vb, pa0, pa1, pa2, pa3); pv_one_i<2, BOFF>(o[2], vb, pa0, pa1, pa2, pa3); pv_one_i<3, BOFF>(o[3], vb, pa0, pa1, pa2, pa3);
; }
	v_mfma_f32_32x32x16_bf16 v[48:63], v[92:95], v[224:227], v[48:63]
	ds_read_b128 v[64:67], v207
	ds_read_b128 v[68:71], v207 offset:8192
	ds_read_b128 v[162:165], v208
	ds_read_b128 v[166:169], v208 offset:8192
	v_exp_f32_e32 v170, v104
	v_exp_f32_e32 v171, v105
	v_exp_f32_e32 v172, v106
	v_exp_f32_e32 v173, v107
	v_exp_f32_e32 v174, v108
	v_exp_f32_e32 v175, v109
	v_exp_f32_e32 v176, v110
	v_exp_f32_e32 v111, v111
	s_waitcnt lgkmcnt(3)
	v_mfma_f32_32x32x16_bf16 v[80:95], v[64:67], v[142:145], 0
	v_exp_f32_e32 v236, v96
	v_add_f32_e32 v96, 0, v184
	v_add_f32_e32 v96, v185, v96
	v_add_f32_e32 v96, v186, v96
	s_waitcnt lgkmcnt(2)
	v_mfma_f32_32x32x16_bf16 v[64:79], v[68:71], v[142:145], 0
	v_add_f32_e32 v96, v187, v96
	v_add_f32_e32 v96, v188, v96
	v_add_f32_e32 v96, v189, v96
	s_waitcnt lgkmcnt(1)
	v_mfma_f32_32x32x16_bf16 v[80:95], v[162:165], v[138:141], v[80:95]
	v_add_f32_e32 v96, v196, v96
	v_add_f32_e32 v96, v197, v96
	v_add_f32_e32 v96, v198, v96
	s_waitcnt lgkmcnt(0)
	v_mfma_f32_32x32x16_bf16 v[64:79], v[166:169], v[138:141], v[64:79]
	ds_read_b128 v[162:165], v209
	ds_read_b128 v[166:169], v209 offset:8192
	v_add_f32_e32 v96, v199, v96
	v_add_f32_e32 v96, v215, v96
	v_add_f32_e32 v96, v216, v96
	v_add_f32_e32 v96, v217, v96
	v_exp_f32_e32 v237, v97
	s_waitcnt lgkmcnt(1)
	v_mfma_f32_32x32x16_bf16 v[80:95], v[162:165], v[112:115], v[80:95]
	v_add_f32_e32 v96, v218, v96
	v_exp_f32_e32 v238, v98
	v_add_f32_e32 v96, v219, v96
	v_exp_f32_e32 v239, v99
	s_waitcnt lgkmcnt(0)
	v_mfma_f32_32x32x16_bf16 v[64:79], v[166:169], v[112:115], v[64:79]
	ds_read_b128 v[162:165], v210
	ds_read_b128 v[166:169], v210 offset:8192
	v_add_f32_e32 v96, v220, v96
	v_exp_f32_e32 v247, v100
	v_add_f32_e32 v96, v236, v96
	v_exp_f32_e32 v248, v101
	s_waitcnt lgkmcnt(1)
	v_mfma_f32_32x32x16_bf16 v[80:95], v[162:165], v[116:119], v[80:95]
	v_add_f32_e32 v96, v237, v96
	v_exp_f32_e32 v249, v102
	v_add_f32_e32 v96, v238, v96
	v_exp_f32_e32 v252, v103
	s_waitcnt lgkmcnt(0)
	v_mfma_f32_32x32x16_bf16 v[64:79], v[166:169], v[116:119], v[64:79]
	ds_read_b128 v[162:165], v190 offset:0
	ds_read_b128 v[166:169], v190 offset:8192
	v_add_f32_e32 v96, v239, v96
	v_add_f32_e32 v96, v247, v96
	v_add_f32_e32 v96, v248, v96
	v_add_f32_e32 v96, v249, v96
	v_add_f32_e32 v96, v252, v96
	v_add_f32_e32 v96, v170, v96
	s_waitcnt lgkmcnt(1)
	v_mfma_f32_32x32x16_bf16 v[80:95], v[162:165], v[120:123], v[80:95]
	v_add_f32_e32 v96, v171, v96
	v_add_f32_e32 v96, v172, v96
	v_add_f32_e32 v96, v173, v96
	v_add_f32_e32 v96, v174, v96
	v_add_f32_e32 v96, v175, v96
	s_waitcnt lgkmcnt(0)
	v_mfma_f32_32x32x16_bf16 v[64:79], v[166:169], v[120:123], v[64:79]
	ds_read_b128 v[162:165], v191 offset:0
	ds_read_b128 v[166:169], v191 offset:8192
	v_add_f32_e32 v96, v176, v96
	v_add_f32_e32 v181, v111, v96
	v_mov_b32_e32 v183, v181
	s_nop 1
	v_permlane32_swap_b32_e32 v181, v183
	v_pk_add_f32 v[96:97], v[180:181], v[182:183]
	s_waitcnt lgkmcnt(1)
	v_mfma_f32_32x32x16_bf16 v[80:95], v[162:165], v[124:127], v[80:95]
	s_nop 0
	v_add_f32_e32 v96, v128, v96
	v_add_f32_e32 v128, v96, v97
	v_cvt_pk_bf16_f32 v96, v184, v185
	v_cvt_pk_bf16_f32 v97, v186, v187
	s_waitcnt lgkmcnt(0)
	v_mfma_f32_32x32x16_bf16 v[64:79], v[166:169], v[124:127], v[64:79]
	ds_read_b128 v[162:165], v192 offset:0
	ds_read_b128 v[166:169], v192 offset:8192
	v_cvt_pk_bf16_f32 v98, v188, v189
	v_cvt_pk_bf16_f32 v99, v196, v197
	v_cvt_pk_bf16_f32 v100, v198, v199
	v_cvt_pk_bf16_f32 v101, v215, v216
	v_cvt_pk_bf16_f32 v102, v217, v218
	v_cvt_pk_bf16_f32 v103, v219, v220
	s_waitcnt lgkmcnt(1)
	v_mfma_f32_32x32x16_bf16 v[80:95], v[162:165], v[130:133], v[80:95]
	v_cvt_pk_bf16_f32 v104, v236, v237
	v_cvt_pk_bf16_f32 v105, v238, v239
	v_cvt_pk_bf16_f32 v106, v247, v248
	v_cvt_pk_bf16_f32 v107, v249, v252
	v_cvt_pk_bf16_f32 v108, v170, v171
	s_waitcnt lgkmcnt(0)
	v_mfma_f32_32x32x16_bf16 v[64:79], v[166:169], v[130:133], v[64:79]
	ds_read_b128 v[162:165], v193 offset:0
	ds_read_b128 v[166:169], v193 offset:8192
	ds_read_b64_tr_b16 v[180:181], v206 offset:0x8000
	ds_read_b64_tr_b16 v[182:183], v206 offset:0x8800
	ds_read_b64_tr_b16 v[184:185], v206 offset:0x9000
	ds_read_b64_tr_b16 v[186:187], v206 offset:0x9800
	ds_read_b64_tr_b16 v[216:217], v206 offset:0xa000
	ds_read_b64_tr_b16 v[218:219], v206 offset:0xa800
	ds_read_b64_tr_b16 v[220:221], v206 offset:0xb000
	ds_read_b64_tr_b16 v[222:223], v206 offset:0xb800
	v_cvt_pk_bf16_f32 v109, v172, v173
	v_cvt_pk_bf16_f32 v110, v174, v175
	v_cvt_pk_bf16_f32 v111, v176, v111
	s_nop 0
	v_permlane32_swap_b32_e32 v96, v98
	v_permlane32_swap_b32_e32 v97, v99
	s_waitcnt lgkmcnt(9)
	v_mfma_f32_32x32x16_bf16 v[80:95], v[162:165], v[134:137], v[80:95]
	v_permlane32_swap_b32_e32 v100, v102
	v_permlane32_swap_b32_e32 v101, v103
	v_permlane32_swap_b32_e32 v104, v106
	v_permlane32_swap_b32_e32 v105, v107
	v_permlane32_swap_b32_e32 v108, v110
	s_waitcnt lgkmcnt(8)
	v_mfma_f32_32x32x16_bf16 v[64:79], v[166:169], v[134:137], v[64:79]
	v_permlane32_swap_b32_e32 v109, v111
	s_waitcnt vmcnt(0)
	ds_write_b128 v211, v[146:149] offset:16384
	s_nop 0
	s_waitcnt lgkmcnt(7)
	v_mfma_f32_32x32x16_bf16 v[0:15], v[96:99], v[180:183], v[0:15]
	ds_read_b64_tr_b16 v[180:181], v206 offset:0x8200
	ds_read_b64_tr_b16 v[182:183], v206 offset:0x8a00
	v_add_co_u32_e32 v166, vcc, s23, v178
	s_nop 1
	v_addc_co_u32_e32 v167, vcc, -1, v179, vcc
	v_add_co_u32_e32 v170, vcc, s24, v178
	s_nop 1
	v_addc_co_u32_e32 v171, vcc, -1, v179, vcc
	s_waitcnt lgkmcnt(7)
; #define SBAR() __builtin_amdgcn_sched_barrier(0)
; __device__ __forceinline__ void partialSM_fixed(f32x16& p0) {
;   for (int r = 0; r < 16; ++r) p0[r] = __builtin_amdgcn_exp2f(p0[r]);
; }
; __device__ __forceinline__ void finishSM(f32x16& p0, f32x16& p1, float alpha, float& l_reg, bf16x8& pa0, bf16x8& pa1, bf16x8& pa2, bf16x8& pa3) {
;   for (int r = 0; r < 16; ++r) p1[r] = __builtin_amdgcn_exp2f(p1[r]);
;   float ps = 0; for (int r = 0; r < 16; ++r) ps += p0[r]; for (int r = 0; r < 16; ++r) ps += p1[r];
;   { auto rr = __builtin_amdgcn_permlane32_swap(__float_as_uint(ps), __float_as_uint(ps), false, false);
;     ps = __uint_as_float(rr[0]) + __uint_as_float(rr[1]); }
;   l_reg = l_reg * alpha + ps;
;     ...
;   PK4(p0, 0, pa0); PK4(p0, 8, pa1); PK4(p1, 0, pa2); PK4(p1, 8, pa3);
;     ...
; }
; template <int D0, int BOFF> __device__ __forceinline__ void pv_one_i(f32x16& od, int vb, bf16x8 pa0, bf16x8 pa1, bf16x8 pa2, bf16x8 pa3) {
;   const s16x4 l0 = tr_read<BOFF + v_rd_off(D0, 0, 0)>(vb), h0 = tr_read<BOFF + v_rd_off(D0, 0, 1)>(vb), l1 = tr_read<BOFF + v_rd_off(D0, 1, 0)>(vb), h1 = tr_read<BOFF + v_rd_off(D0, 1, 1)>(vb);
;   const s16x4 l2 = tr_read<BOFF + v_rd_off(D0, 2, 0)>(vb), h2 = tr_read<BOFF + v_rd_off(D0, 2, 1)>(vb), l3 = tr_read<BOFF + v_rd_off(D0, 3, 0)>(vb), h3 = tr_read<BOFF + v_rd_off(D0, 3, 1)>(vb);
;   asm volatile("s_waitcnt lgkmcnt(0)" ::: "memory"); SBAR();
;     ...
;   od = __builtin_amdgcn_mfma_f32_32x32x16_bf16(pa0, PK(l0, h0), od, 0, 0, 0);
;   od = __builtin_amdgcn_mfma_f32_32x32x16_bf16(pa1, PK(l1, h1), od, 0, 0, 0);
;   od = __builtin_amdgcn_mfma_f32_32x32x16_bf16(pa2, PK(l2, h2), od, 0, 0, 0);
;   od = __builtin_amdgcn_mfma_f32_32x32x16_bf16(pa3, PK(l3, h3), od, 0, 0, 0);
;     ...
; }
; template <int BOFF> __device__ __forceinline__ void pv_i(f32x16* o, int vb, bf16x8 pa0, bf16x8 pa1, bf16x8 pa2, bf16x8 pa3) {
;   pv_one_i<0, BOFF>(o[0], vb, pa0, pa1, pa2, pa3); pv_one_i<1, BOFF>(o[1], vb, pa0, pa1, pa2, pa3); pv_one_i<2, BOFF>(o[2], vb, pa0, pa1, pa2, pa3); pv_one_i<3, BOFF>(o[3], vb, pa0, pa1, pa2, pa3);
; }
	v_mfma_f32_32x32x16_bf16 v[0:15], v[100:103], v[184:187], v[0:15]
	ds_read_b64_tr_b16 v[184:185], v206 offset:0x9200
	ds_read_b64_tr_b16 v[186:187], v206 offset:0x9a00
	global_load_dwordx4 v[162:165], v[166:167], off
	s_nop 0
	global_load_dwordx4 v[166:169], v[166:167], off offset:-512
	s_nop 0
	global_load_dwordx4 v[174:177], v[170:171], off
	s_nop 0
	global_load_dwordx4 v[170:173], v[170:171], off offset:-512
	s_waitcnt lgkmcnt(7)
	v_mfma_f32_32x32x16_bf16 v[0:15], v[104:107], v[216:219], v[0:15]
	ds_read_b64_tr_b16 v[216:217], v206 offset:0xa200
	ds_read_b64_tr_b16 v[218:219], v206 offset:0xaa00
	s_waitcnt lgkmcnt(7)
	v_mfma_f32_32x32x16_bf16 v[0:15], v[108:111], v[220:223], v[0:15]
	ds_read_b64_tr_b16 v[220:221], v206 offset:0xb200
	ds_read_b64_tr_b16 v[222:223], v206 offset:0xba00
	ds_write_b128 v212, v[158:161] offset:16384
	s_waitcnt lgkmcnt(7)
	v_mfma_f32_32x32x16_bf16 v[16:31], v[96:99], v[180:183], v[16:31]
	ds_read_b64_tr_b16 v[180:181], v206 offset:0x8400
	ds_read_b64_tr_b16 v[182:183], v206 offset:0x8c00
	s_waitcnt lgkmcnt(7)
	v_mfma_f32_32x32x16_bf16 v[16:31], v[100:103], v[184:187], v[16:31]
	ds_read_b64_tr_b16 v[184:185], v206 offset:0x9400
	ds_read_b64_tr_b16 v[186:187], v206 offset:0x9c00
	s_waitcnt lgkmcnt(7)
	v_mfma_f32_32x32x16_bf16 v[16:31], v[104:107], v[216:219], v[16:31]
	ds_read_b64_tr_b16 v[216:217], v206 offset:0xa400
	ds_read_b64_tr_b16 v[218:219], v206 offset:0xac00
	s_waitcnt lgkmcnt(7)
	v_mfma_f32_32x32x16_bf16 v[16:31], v[108:111], v[220:223], v[16:31]
	ds_read_b64_tr_b16 v[220:221], v206 offset:0xb400
	ds_read_b64_tr_b16 v[222:223], v206 offset:0xbc00
	ds_write_b128 v213, v[150:153] offset:16384
	s_waitcnt lgkmcnt(7)
	v_mfma_f32_32x32x16_bf16 v[32:47], v[96:99], v[180:183], v[32:47]
	ds_read_b64_tr_b16 v[180:181], v206 offset:0x8600
	ds_read_b64_tr_b16 v[182:183], v206 offset:0x8e00
	s_waitcnt lgkmcnt(7)
	v_mfma_f32_32x32x16_bf16 v[32:47], v[100:103], v[184:187], v[32:47]
	ds_read_b64_tr_b16 v[184:185], v206 offset:0x9600
	ds_read_b64_tr_b16 v[186:187], v206 offset:0x9e00
	s_waitcnt lgkmcnt(7)
	v_mfma_f32_32x32x16_bf16 v[32:47], v[104:107], v[216:219], v[32:47]
	ds_read_b64_tr_b16 v[216:217], v206 offset:0xa600
	ds_read_b64_tr_b16 v[218:219], v206 offset:0xae00
	s_waitcnt lgkmcnt(7)
	v_mfma_f32_32x32x16_bf16 v[32:47], v[108:111], v[220:223], v[32:47]
	ds_read_b64_tr_b16 v[220:221], v206 offset:0xb600
	ds_read_b64_tr_b16 v[222:223], v206 offset:0xbe00
	ds_write_b128 v214, v[154:157] offset:16384
	s_waitcnt lgkmcnt(7)
	v_mfma_f32_32x32x16_bf16 v[48:63], v[96:99], v[180:183], v[48:63]
	v_exp_f32_e32 v215, v92
	s_waitcnt vmcnt(4)
	v_exp_f32_e32 v181, v80
	v_exp_f32_e32 v183, v81
	v_exp_f32_e32 v188, v86
	v_exp_f32_e32 v189, v87
	v_exp_f32_e32 v196, v88
	s_waitcnt lgkmcnt(5)
	v_mfma_f32_32x32x16_bf16 v[48:63], v[100:103], v[184:187], v[48:63]
	v_exp_f32_e32 v184, v82
	v_exp_f32_e32 v185, v83
	v_exp_f32_e32 v186, v84
	v_exp_f32_e32 v187, v85
	v_exp_f32_e32 v197, v89
	v_exp_f32_e32 v198, v90
	v_exp_f32_e32 v199, v91
	s_waitcnt lgkmcnt(3)
	v_mfma_f32_32x32x16_bf16 v[48:63], v[104:107], v[216:219], v[48:63]
	v_exp_f32_e32 v216, v93
	v_exp_f32_e32 v217, v94
	v_exp_f32_e32 v218, v95
	s_waitcnt lgkmcnt(0)
	s_barrier
	v_mfma_f32_32x32x16_bf16 v[48:63], v[108:111], v[220:223], v[48:63]
	ds_read_b128 v[80:83], v207 offset:16384
	ds_read_b128 v[96:99], v207 offset:24576
	ds_read_b128 v[146:149], v208 offset:16384
	ds_read_b128 v[150:153], v208 offset:24576
	v_exp_f32_e32 v154, v72
	v_exp_f32_e32 v155, v73
	v_exp_f32_e32 v156, v74
	v_exp_f32_e32 v157, v75
	v_exp_f32_e32 v158, v76
	v_exp_f32_e32 v159, v77
	v_exp_f32_e32 v160, v78
	v_exp_f32_e32 v79, v79
	s_waitcnt lgkmcnt(3)
	v_mfma_f32_32x32x16_bf16 v[80:95], v[80:83], v[142:145], 0
	v_exp_f32_e32 v236, v64
	v_add_f32_e32 v64, 0, v181
	v_add_f32_e32 v64, v183, v64
	v_add_f32_e32 v64, v184, v64
	s_waitcnt lgkmcnt(2)
	v_mfma_f32_32x32x16_bf16 v[96:111], v[96:99], v[142:145], 0
	v_add_f32_e32 v64, v185, v64
	v_add_f32_e32 v64, v186, v64
	v_add_f32_e32 v64, v187, v64
	s_waitcnt lgkmcnt(1)
	v_mfma_f32_32x32x16_bf16 v[80:95], v[146:149], v[138:141], v[80:95]
	v_add_f32_e32 v64, v188, v64
	v_add_f32_e32 v64, v189, v64
	v_add_f32_e32 v64, v196, v64
	s_waitcnt lgkmcnt(0)
	v_mfma_f32_32x32x16_bf16 v[96:111], v[150:153], v[138:141], v[96:111]
	ds_read_b128 v[146:149], v209 offset:16384
	ds_read_b128 v[150:153], v209 offset:24576
	v_add_f32_e32 v64, v197, v64
	v_add_f32_e32 v64, v198, v64
	v_add_f32_e32 v64, v199, v64
	v_add_f32_e32 v64, v215, v64
	v_exp_f32_e32 v237, v65
	s_waitcnt lgkmcnt(1)
	v_mfma_f32_32x32x16_bf16 v[80:95], v[146:149], v[112:115], v[80:95]
	v_add_f32_e32 v64, v216, v64
	v_exp_f32_e32 v238, v66
	v_add_f32_e32 v64, v217, v64
	v_exp_f32_e32 v239, v67
	s_waitcnt lgkmcnt(0)
	v_mfma_f32_32x32x16_bf16 v[96:111], v[150:153], v[112:115], v[96:111]
	ds_read_b128 v[146:149], v210 offset:16384
	ds_read_b128 v[150:153], v210 offset:24576
	v_add_f32_e32 v64, v218, v64
	v_exp_f32_e32 v247, v68
	v_add_f32_e32 v64, v236, v64
	v_exp_f32_e32 v248, v69
	s_waitcnt lgkmcnt(1)
	v_mfma_f32_32x32x16_bf16 v[80:95], v[146:149], v[116:119], v[80:95]
	v_add_f32_e32 v64, v237, v64
	v_exp_f32_e32 v249, v70
	v_add_f32_e32 v64, v238, v64
	v_exp_f32_e32 v252, v71
	s_waitcnt lgkmcnt(0)
	v_mfma_f32_32x32x16_bf16 v[96:111], v[150:153], v[116:119], v[96:111]
	ds_read_b128 v[146:149], v190 offset:16384
	ds_read_b128 v[150:153], v190 offset:24576
	v_add_f32_e32 v64, v239, v64
	v_add_f32_e32 v64, v247, v64
	v_add_f32_e32 v64, v248, v64
	v_add_f32_e32 v64, v249, v64
	v_add_f32_e32 v64, v252, v64
	v_add_f32_e32 v64, v154, v64
	s_waitcnt lgkmcnt(1)
; #define SBAR() __builtin_amdgcn_sched_barrier(0)
; __device__ __forceinline__ void partialSM_fixed(f32x16& p0) {
;   for (int r = 0; r < 16; ++r) p0[r] = __builtin_amdgcn_exp2f(p0[r]);
; }
; __device__ __forceinline__ void finishSM(f32x16& p0, f32x16& p1, float alpha, float& l_reg, bf16x8& pa0, bf16x8& pa1, bf16x8& pa2, bf16x8& pa3) {
;   for (int r = 0; r < 16; ++r) p1[r] = __builtin_amdgcn_exp2f(p1[r]);
;   float ps = 0; for (int r = 0; r < 16; ++r) ps += p0[r]; for (int r = 0; r < 16; ++r) ps += p1[r];
;   { auto rr = __builtin_amdgcn_permlane32_swap(__float_as_uint(ps), __float_as_uint(ps), false, false);
;     ps = __uint_as_float(rr[0]) + __uint_as_float(rr[1]); }
;   l_reg = l_reg * alpha + ps;
;     ...
;   PK4(p0, 0, pa0); PK4(p0, 8, pa1); PK4(p1, 0, pa2); PK4(p1, 8, pa3);
;     ...
; }
; template <int D0, int BOFF> __device__ __forceinline__ void pv_one_i(f32x16& od, int vb, bf16x8 pa0, bf16x8 pa1, bf16x8 pa2, bf16x8 pa3) {
;   const s16x4 l0 = tr_read<BOFF + v_rd_off(D0, 0, 0)>(vb), h0 = tr_read<BOFF + v_rd_off(D0, 0, 1)>(vb), l1 = tr_read<BOFF + v_rd_off(D0, 1, 0)>(vb), h1 = tr_read<BOFF + v_rd_off(D0, 1, 1)>(vb);
;   const s16x4 l2 = tr_read<BOFF + v_rd_off(D0, 2, 0)>(vb), h2 = tr_read<BOFF + v_rd_off(D0, 2, 1)>(vb), l3 = tr_read<BOFF + v_rd_off(D0, 3, 0)>(vb), h3 = tr_read<BOFF + v_rd_off(D0, 3, 1)>(vb);
;   asm volatile("s_waitcnt lgkmcnt(0)" ::: "memory"); SBAR();
;     ...
;   od = __builtin_amdgcn_mfma_f32_32x32x16_bf16(pa0, PK(l0, h0), od, 0, 0, 0);
;   od = __builtin_amdgcn_mfma_f32_32x32x16_bf16(pa1, PK(l1, h1), od, 0, 0, 0);
;   od = __builtin_amdgcn_mfma_f32_32x32x16_bf16(pa2, PK(l2, h2), od, 0, 0, 0);
;   od = __builtin_amdgcn_mfma_f32_32x32x16_bf16(pa3, PK(l3, h3), od, 0, 0, 0);
;     ...
; }
; template <int BOFF> __device__ __forceinline__ void pv_i(f32x16* o, int vb, bf16x8 pa0, bf16x8 pa1, bf16x8 pa2, bf16x8 pa3) {
;   pv_one_i<0, BOFF>(o[0], vb, pa0, pa1, pa2, pa3); pv_one_i<1, BOFF>(o[1], vb, pa0, pa1, pa2, pa3); pv_one_i<2, BOFF>(o[2], vb, pa0, pa1, pa2, pa3); pv_one_i<3, BOFF>(o[3], vb, pa0, pa1, pa2, pa3);
; }
	v_mfma_f32_32x32x16_bf16 v[80:95], v[146:149], v[120:123], v[80:95]
	v_add_f32_e32 v64, v155, v64
	v_add_f32_e32 v64, v156, v64
	v_add_f32_e32 v64, v157, v64
	v_add_f32_e32 v64, v158, v64
	v_add_f32_e32 v64, v159, v64
	s_waitcnt lgkmcnt(0)
	v_mfma_f32_32x32x16_bf16 v[96:111], v[150:153], v[120:123], v[96:111]
	ds_read_b128 v[146:149], v191 offset:16384
	ds_read_b128 v[150:153], v191 offset:24576
	v_add_f32_e32 v64, v160, v64
	v_add_f32_e32 v180, v79, v64
	v_cvt_pk_bf16_f32 v64, v181, v183
	v_cvt_pk_bf16_f32 v65, v184, v185
	v_cvt_pk_bf16_f32 v66, v186, v187
	v_cvt_pk_bf16_f32 v67, v188, v189
	s_waitcnt lgkmcnt(1)
	v_mfma_f32_32x32x16_bf16 v[80:95], v[146:149], v[124:127], v[80:95]
	v_cvt_pk_bf16_f32 v68, v196, v197
	v_cvt_pk_bf16_f32 v69, v198, v199
	v_cvt_pk_bf16_f32 v70, v215, v216
	v_cvt_pk_bf16_f32 v71, v217, v218
	v_cvt_pk_bf16_f32 v72, v236, v237
	s_waitcnt lgkmcnt(0)
	v_mfma_f32_32x32x16_bf16 v[96:111], v[150:153], v[124:127], v[96:111]
	ds_read_b128 v[146:149], v192 offset:16384
	ds_read_b128 v[150:153], v192 offset:24576
	v_cvt_pk_bf16_f32 v73, v238, v239
	v_cvt_pk_bf16_f32 v74, v247, v248
	v_cvt_pk_bf16_f32 v75, v249, v252
	v_cvt_pk_bf16_f32 v76, v154, v155
	v_cvt_pk_bf16_f32 v77, v156, v157
	v_cvt_pk_bf16_f32 v78, v158, v159
	s_waitcnt lgkmcnt(1)
	v_mfma_f32_32x32x16_bf16 v[80:95], v[146:149], v[130:133], v[80:95]
	v_cvt_pk_bf16_f32 v79, v160, v79
	v_mov_b32_e32 v182, v180
	v_permlane32_swap_b32_e32 v64, v66
	v_permlane32_swap_b32_e32 v65, v67
	v_permlane32_swap_b32_e32 v68, v70
	s_waitcnt lgkmcnt(0)
	v_mfma_f32_32x32x16_bf16 v[96:111], v[150:153], v[130:133], v[96:111]
	ds_read_b128 v[146:149], v193 offset:16384
	ds_read_b128 v[150:153], v193 offset:24576
	ds_read_b64_tr_b16 v[184:185], v206 offset:0
	ds_read_b64_tr_b16 v[186:187], v206 offset:0x800
	ds_read_b64_tr_b16 v[216:217], v206 offset:0x1000
	ds_read_b64_tr_b16 v[218:219], v206 offset:0x1800
	ds_read_b64_tr_b16 v[220:221], v206 offset:0x2000
	ds_read_b64_tr_b16 v[222:223], v206 offset:0x2800
	ds_read_b64_tr_b16 v[224:225], v206 offset:0x3000
	ds_read_b64_tr_b16 v[226:227], v206 offset:0x3800
	v_permlane32_swap_b32_e32 v69, v71
	v_permlane32_swap_b32_e32 v72, v74
	v_permlane32_swap_b32_e32 v73, v75
	v_permlane32_swap_b32_e32 v76, v78
	v_permlane32_swap_b32_e32 v77, v79
	v_permlane32_swap_b32_e32 v180, v182
	s_waitcnt lgkmcnt(9)
	v_mfma_f32_32x32x16_bf16 v[80:95], v[146:149], v[134:137], v[80:95]
	s_waitcnt lgkmcnt(8)
	v_mfma_f32_32x32x16_bf16 v[96:111], v[150:153], v[134:137], v[96:111]
	s_waitcnt vmcnt(0)
	ds_write_b128 v211, v[162:165] offset:32768
	s_nop 0
	s_waitcnt lgkmcnt(7)
	v_mfma_f32_32x32x16_bf16 v[0:15], v[64:67], v[184:187], v[0:15]
	ds_read_b64_tr_b16 v[184:185], v206 offset:0x200
	ds_read_b64_tr_b16 v[186:187], v206 offset:0xa00
	v_add_co_u32_e32 v150, vcc, s25, v178
	s_nop 1
	v_addc_co_u32_e32 v151, vcc, -1, v179, vcc
	v_add_co_u32_e32 v154, vcc, s45, v178
	s_nop 1
	v_addc_co_u32_e32 v155, vcc, -1, v179, vcc
	s_waitcnt lgkmcnt(7)
	v_mfma_f32_32x32x16_bf16 v[0:15], v[68:71], v[216:219], v[0:15]
	ds_read_b64_tr_b16 v[216:217], v206 offset:0x1200
	ds_read_b64_tr_b16 v[218:219], v206 offset:0x1a00
	global_load_dwordx4 v[146:149], v[150:151], off
	s_nop 0
	global_load_dwordx4 v[150:153], v[150:151], off offset:-512
	s_nop 0
	global_load_dwordx4 v[158:161], v[154:155], off
	s_nop 0
	global_load_dwordx4 v[154:157], v[154:155], off offset:-512
	s_waitcnt lgkmcnt(7)
	v_mfma_f32_32x32x16_bf16 v[0:15], v[72:75], v[220:223], v[0:15]
	ds_read_b64_tr_b16 v[220:221], v206 offset:0x2200
	ds_read_b64_tr_b16 v[222:223], v206 offset:0x2a00
	s_waitcnt lgkmcnt(7)
	v_mfma_f32_32x32x16_bf16 v[0:15], v[76:79], v[224:227], v[0:15]
	ds_read_b64_tr_b16 v[224:225], v206 offset:0x3200
	ds_read_b64_tr_b16 v[226:227], v206 offset:0x3a00
	ds_write_b128 v212, v[174:177] offset:32768
	s_waitcnt lgkmcnt(7)
	v_mfma_f32_32x32x16_bf16 v[16:31], v[64:67], v[184:187], v[16:31]
	ds_read_b64_tr_b16 v[184:185], v206 offset:0x400
	ds_read_b64_tr_b16 v[186:187], v206 offset:0xc00
	s_waitcnt lgkmcnt(7)
	v_mfma_f32_32x32x16_bf16 v[16:31], v[68:71], v[216:219], v[16:31]
	ds_read_b64_tr_b16 v[216:217], v206 offset:0x1400
	ds_read_b64_tr_b16 v[218:219], v206 offset:0x1c00
	s_waitcnt lgkmcnt(7)
	v_mfma_f32_32x32x16_bf16 v[16:31], v[72:75], v[220:223], v[16:31]
	ds_read_b64_tr_b16 v[220:221], v206 offset:0x2400
	ds_read_b64_tr_b16 v[222:223], v206 offset:0x2c00
	s_waitcnt lgkmcnt(7)
	v_mfma_f32_32x32x16_bf16 v[16:31], v[76:79], v[224:227], v[16:31]
	ds_read_b64_tr_b16 v[224:225], v206 offset:0x3400
	ds_read_b64_tr_b16 v[226:227], v206 offset:0x3c00
	ds_write_b128 v213, v[166:169] offset:32768
	s_waitcnt lgkmcnt(7)
	v_mfma_f32_32x32x16_bf16 v[32:47], v[64:67], v[184:187], v[32:47]
	ds_read_b64_tr_b16 v[184:185], v206 offset:0x600
	ds_read_b64_tr_b16 v[186:187], v206 offset:0xe00
	s_waitcnt lgkmcnt(7)
	v_mfma_f32_32x32x16_bf16 v[32:47], v[68:71], v[216:219], v[32:47]
	ds_read_b64_tr_b16 v[216:217], v206 offset:0x1600
	ds_read_b64_tr_b16 v[218:219], v206 offset:0x1e00
	s_waitcnt lgkmcnt(7)
	v_mfma_f32_32x32x16_bf16 v[32:47], v[72:75], v[220:223], v[32:47]
	ds_read_b64_tr_b16 v[220:221], v206 offset:0x2600
	ds_read_b64_tr_b16 v[222:223], v206 offset:0x2e00
	s_waitcnt lgkmcnt(7)
	v_mfma_f32_32x32x16_bf16 v[32:47], v[76:79], v[224:227], v[32:47]
	ds_read_b64_tr_b16 v[224:225], v206 offset:0x3600
	ds_read_b64_tr_b16 v[226:227], v206 offset:0x3e00
	ds_write_b128 v214, v[170:173] offset:32768
	s_waitcnt lgkmcnt(7)
	v_mfma_f32_32x32x16_bf16 v[48:63], v[64:67], v[184:187], v[48:63]
	v_exp_f32_e32 v215, v90
	s_waitcnt vmcnt(4)
	v_exp_f32_e32 v184, v80
	v_exp_f32_e32 v185, v81
	v_exp_f32_e32 v186, v82
	v_exp_f32_e32 v187, v83
	v_exp_f32_e32 v188, v84
	s_waitcnt lgkmcnt(5)
	v_mfma_f32_32x32x16_bf16 v[48:63], v[68:71], v[216:219], v[48:63]
	v_exp_f32_e32 v219, v94
	v_exp_f32_e32 v189, v85
	v_exp_f32_e32 v196, v86
	v_exp_f32_e32 v197, v87
	v_exp_f32_e32 v198, v88
	v_exp_f32_e32 v199, v89
	v_exp_f32_e32 v216, v91
	s_waitcnt lgkmcnt(3)
	v_mfma_f32_32x32x16_bf16 v[48:63], v[72:75], v[220:223], v[48:63]
	v_exp_f32_e32 v220, v95
	v_exp_f32_e32 v217, v92
	v_exp_f32_e32 v218, v93
	s_waitcnt lgkmcnt(0)
	s_barrier
; #define SBAR() __builtin_amdgcn_sched_barrier(0)
; template <int BOFF> __device__ __forceinline__ void qkt_i(f32x16& p0, f32x16& p1, const int (&kb)[4], const bf16x8* qr) {
;   p0 = f32x16{}; p1 = f32x16{};
; #pragma unroll
;   for (int d0 = 0; d0 < 8; ++d0) { const int off = BOFF + (d0 >> 2) * 128;
;     const bf16x8 b0 = LDSV(kb[d0 & 3] + off), b1 = LDSV(kb[d0 & 3] + off + 8192);
;     p0 = __builtin_amdgcn_mfma_f32_32x32x16_bf16(b0, qr[d0], p0, 0, 0, 0);
;     p1 = __builtin_amdgcn_mfma_f32_32x32x16_bf16(b1, qr[d0], p1, 0, 0, 0); }
; }
; template <int D0, int BOFF> __device__ __forceinline__ void pv_one_i(f32x16& od, int vb, bf16x8 pa0, bf16x8 pa1, bf16x8 pa2, bf16x8 pa3) {
;   const s16x4 l0 = tr_read<BOFF + v_rd_off(D0, 0, 0)>(vb), h0 = tr_read<BOFF + v_rd_off(D0, 0, 1)>(vb), l1 = tr_read<BOFF + v_rd_off(D0, 1, 0)>(vb), h1 = tr_read<BOFF + v_rd_off(D0, 1, 1)>(vb);
;   const s16x4 l2 = tr_read<BOFF + v_rd_off(D0, 2, 0)>(vb), h2 = tr_read<BOFF + v_rd_off(D0, 2, 1)>(vb), l3 = tr_read<BOFF + v_rd_off(D0, 3, 0)>(vb), h3 = tr_read<BOFF + v_rd_off(D0, 3, 1)>(vb);
;   asm volatile("s_waitcnt lgkmcnt(0)" ::: "memory"); SBAR();
;     ...
;   od = __builtin_amdgcn_mfma_f32_32x32x16_bf16(pa0, PK(l0, h0), od, 0, 0, 0);
;   od = __builtin_amdgcn_mfma_f32_32x32x16_bf16(pa1, PK(l1, h1), od, 0, 0, 0);
;   od = __builtin_amdgcn_mfma_f32_32x32x16_bf16(pa2, PK(l2, h2), od, 0, 0, 0);
;   od = __builtin_amdgcn_mfma_f32_32x32x16_bf16(pa3, PK(l3, h3), od, 0, 0, 0);
;     ...
; }
; template <int BOFF> __device__ __forceinline__ void pv_i(f32x16* o, int vb, bf16x8 pa0, bf16x8 pa1, bf16x8 pa2, bf16x8 pa3) {
;   pv_one_i<0, BOFF>(o[0], vb, pa0, pa1, pa2, pa3); pv_one_i<1, BOFF>(o[1], vb, pa0, pa1, pa2, pa3); pv_one_i<2, BOFF>(o[2], vb, pa0, pa1, pa2, pa3); pv_one_i<3, BOFF>(o[3], vb, pa0, pa1, pa2, pa3);
; }
	v_mfma_f32_32x32x16_bf16 v[48:63], v[76:79], v[224:227], v[48:63]
	ds_read_b128 v[64:67], v207 offset:32768
	ds_read_b128 v[80:83], v207 offset:40960
	ds_read_b128 v[162:165], v208 offset:32768
	ds_read_b128 v[166:169], v208 offset:40960
	v_exp_f32_e32 v170, v104
	v_exp_f32_e32 v171, v105
	v_exp_f32_e32 v172, v106
	v_exp_f32_e32 v173, v107
	v_exp_f32_e32 v174, v108
	v_exp_f32_e32 v175, v109
	v_exp_f32_e32 v176, v110
	v_exp_f32_e32 v111, v111
	s_waitcnt lgkmcnt(3)
	v_mfma_f32_32x32x16_bf16 v[64:79], v[64:67], v[142:145], 0
	v_exp_f32_e32 v236, v96
	v_add_f32_e32 v96, 0, v184
	v_add_f32_e32 v96, v185, v96
	v_add_f32_e32 v96, v186, v96
	s_waitcnt lgkmcnt(2)
	v_mfma_f32_32x32x16_bf16 v[80:95], v[80:83], v[142:145], 0
	v_add_f32_e32 v96, v187, v96
	v_add_f32_e32 v96, v188, v96
	v_add_f32_e32 v96, v189, v96
	s_waitcnt lgkmcnt(1)
	v_mfma_f32_32x32x16_bf16 v[64:79], v[162:165], v[138:141], v[64:79]
	v_add_f32_e32 v96, v196, v96
	v_add_f32_e32 v96, v197, v96
	v_add_f32_e32 v96, v198, v96
	s_waitcnt lgkmcnt(0)
	v_mfma_f32_32x32x16_bf16 v[80:95], v[166:169], v[138:141], v[80:95]
	ds_read_b128 v[162:165], v209 offset:32768
	ds_read_b128 v[166:169], v209 offset:40960
	v_add_f32_e32 v96, v199, v96
	v_add_f32_e32 v96, v215, v96
	v_add_f32_e32 v96, v216, v96
	v_add_f32_e32 v96, v217, v96
	v_exp_f32_e32 v237, v97
	s_waitcnt lgkmcnt(1)
	v_mfma_f32_32x32x16_bf16 v[64:79], v[162:165], v[112:115], v[64:79]
	v_add_f32_e32 v96, v218, v96
	v_exp_f32_e32 v238, v98
	v_add_f32_e32 v96, v219, v96
	v_exp_f32_e32 v239, v99
	s_waitcnt lgkmcnt(0)
	v_mfma_f32_32x32x16_bf16 v[80:95], v[166:169], v[112:115], v[80:95]
	ds_read_b128 v[162:165], v210 offset:32768
	ds_read_b128 v[166:169], v210 offset:40960
	v_add_f32_e32 v96, v220, v96
	v_exp_f32_e32 v247, v100
	v_add_f32_e32 v96, v236, v96
	v_exp_f32_e32 v248, v101
	s_waitcnt lgkmcnt(1)
	v_mfma_f32_32x32x16_bf16 v[64:79], v[162:165], v[116:119], v[64:79]
	v_add_f32_e32 v96, v237, v96
	v_exp_f32_e32 v249, v102
	v_add_f32_e32 v96, v238, v96
	v_exp_f32_e32 v252, v103
	s_waitcnt lgkmcnt(0)
	v_mfma_f32_32x32x16_bf16 v[80:95], v[166:169], v[116:119], v[80:95]
	ds_read_b128 v[162:165], v190 offset:32768
	ds_read_b128 v[166:169], v190 offset:40960
	v_add_f32_e32 v96, v239, v96
	v_add_f32_e32 v96, v247, v96
	v_add_f32_e32 v96, v248, v96
	v_add_f32_e32 v96, v249, v96
	v_add_f32_e32 v96, v252, v96
	v_add_f32_e32 v96, v170, v96
	s_waitcnt lgkmcnt(1)
	v_mfma_f32_32x32x16_bf16 v[64:79], v[162:165], v[120:123], v[64:79]
	v_add_f32_e32 v96, v171, v96
	v_add_f32_e32 v96, v172, v96
	v_add_f32_e32 v96, v173, v96
	v_add_f32_e32 v96, v174, v96
	v_add_f32_e32 v96, v175, v96
	s_waitcnt lgkmcnt(0)
	v_mfma_f32_32x32x16_bf16 v[80:95], v[166:169], v[120:123], v[80:95]
	ds_read_b128 v[162:165], v191 offset:32768
	ds_read_b128 v[166:169], v191 offset:40960
	v_add_f32_e32 v96, v176, v96
	v_add_f32_e32 v181, v111, v96
	v_mov_b32_e32 v183, v181
	s_nop 1
	v_permlane32_swap_b32_e32 v181, v183
	v_pk_add_f32 v[96:97], v[180:181], v[182:183]
	s_waitcnt lgkmcnt(1)
	v_mfma_f32_32x32x16_bf16 v[64:79], v[162:165], v[124:127], v[64:79]
	s_nop 0
	v_add_f32_e32 v96, v128, v96
	v_add_f32_e32 v128, v96, v97
	v_cvt_pk_bf16_f32 v96, v184, v185
	v_cvt_pk_bf16_f32 v97, v186, v187
	s_waitcnt lgkmcnt(0)
	v_mfma_f32_32x32x16_bf16 v[80:95], v[166:169], v[124:127], v[80:95]
	ds_read_b128 v[162:165], v192 offset:32768
	ds_read_b128 v[166:169], v192 offset:40960
	v_cvt_pk_bf16_f32 v98, v188, v189
	v_cvt_pk_bf16_f32 v99, v196, v197
	v_cvt_pk_bf16_f32 v100, v198, v199
	v_cvt_pk_bf16_f32 v101, v215, v216
	v_cvt_pk_bf16_f32 v102, v217, v218
	v_cvt_pk_bf16_f32 v103, v219, v220
	s_waitcnt lgkmcnt(1)
	v_mfma_f32_32x32x16_bf16 v[64:79], v[162:165], v[130:133], v[64:79]
	v_cvt_pk_bf16_f32 v104, v236, v237
	v_cvt_pk_bf16_f32 v105, v238, v239
	v_cvt_pk_bf16_f32 v106, v247, v248
	v_cvt_pk_bf16_f32 v107, v249, v252
	v_cvt_pk_bf16_f32 v108, v170, v171
	s_waitcnt lgkmcnt(0)
	v_mfma_f32_32x32x16_bf16 v[80:95], v[166:169], v[130:133], v[80:95]
	ds_read_b128 v[162:165], v193 offset:32768
	ds_read_b128 v[166:169], v193 offset:40960
	ds_read_b64_tr_b16 v[180:181], v206 offset:0x4000
	ds_read_b64_tr_b16 v[182:183], v206 offset:0x4800
	ds_read_b64_tr_b16 v[184:185], v206 offset:0x5000
	ds_read_b64_tr_b16 v[186:187], v206 offset:0x5800
	ds_read_b64_tr_b16 v[216:217], v206 offset:0x6000
	ds_read_b64_tr_b16 v[218:219], v206 offset:0x6800
	ds_read_b64_tr_b16 v[220:221], v206 offset:0x7000
	ds_read_b64_tr_b16 v[222:223], v206 offset:0x7800
	v_cvt_pk_bf16_f32 v109, v172, v173
	v_cvt_pk_bf16_f32 v110, v174, v175
	v_cvt_pk_bf16_f32 v111, v176, v111
	s_nop 0
	v_permlane32_swap_b32_e32 v96, v98
	v_permlane32_swap_b32_e32 v97, v99
	s_waitcnt lgkmcnt(9)
	v_mfma_f32_32x32x16_bf16 v[64:79], v[162:165], v[134:137], v[64:79]
	v_permlane32_swap_b32_e32 v100, v102
	v_permlane32_swap_b32_e32 v101, v103
	v_permlane32_swap_b32_e32 v104, v106
	v_permlane32_swap_b32_e32 v105, v107
	v_permlane32_swap_b32_e32 v108, v110
	s_waitcnt lgkmcnt(8)
	v_mfma_f32_32x32x16_bf16 v[80:95], v[166:169], v[134:137], v[80:95]
	v_permlane32_swap_b32_e32 v109, v111
	s_waitcnt vmcnt(0)
	ds_write_b128 v211, v[146:149]
	s_nop 0
	s_waitcnt lgkmcnt(7)
	v_mfma_f32_32x32x16_bf16 v[0:15], v[96:99], v[180:183], v[0:15]
	ds_read_b64_tr_b16 v[180:181], v206 offset:0x4200
	ds_read_b64_tr_b16 v[182:183], v206 offset:0x4a00
	v_add_co_u32_e32 v166, vcc, s52, v178
	s_nop 1
	v_addc_co_u32_e32 v167, vcc, -1, v179, vcc
	v_add_co_u32_e32 v170, vcc, s53, v178
	s_nop 1
	v_addc_co_u32_e32 v171, vcc, -1, v179, vcc
	s_waitcnt lgkmcnt(7)
; #define SBAR() __builtin_amdgcn_sched_barrier(0)
; __device__ __forceinline__ void partialSM_fixed(f32x16& p0) {
;   for (int r = 0; r < 16; ++r) p0[r] = __builtin_amdgcn_exp2f(p0[r]);
; }
; __device__ __forceinline__ void finishSM(f32x16& p0, f32x16& p1, float alpha, float& l_reg, bf16x8& pa0, bf16x8& pa1, bf16x8& pa2, bf16x8& pa3) {
;   for (int r = 0; r < 16; ++r) p1[r] = __builtin_amdgcn_exp2f(p1[r]);
;   float ps = 0; for (int r = 0; r < 16; ++r) ps += p0[r]; for (int r = 0; r < 16; ++r) ps += p1[r];
;   { auto rr = __builtin_amdgcn_permlane32_swap(__float_as_uint(ps), __float_as_uint(ps), false, false);
;     ps = __uint_as_float(rr[0]) + __uint_as_float(rr[1]); }
;   l_reg = l_reg * alpha + ps;
;     ...
;   PK4(p0, 0, pa0); PK4(p0, 8, pa1); PK4(p1, 0, pa2); PK4(p1, 8, pa3);
;     ...
; }
; template <int D0, int BOFF> __device__ __forceinline__ void pv_one_i(f32x16& od, int vb, bf16x8 pa0, bf16x8 pa1, bf16x8 pa2, bf16x8 pa3) {
;   const s16x4 l0 = tr_read<BOFF + v_rd_off(D0, 0, 0)>(vb), h0 = tr_read<BOFF + v_rd_off(D0, 0, 1)>(vb), l1 = tr_read<BOFF + v_rd_off(D0, 1, 0)>(vb), h1 = tr_read<BOFF + v_rd_off(D0, 1, 1)>(vb);
;   const s16x4 l2 = tr_read<BOFF + v_rd_off(D0, 2, 0)>(vb), h2 = tr_read<BOFF + v_rd_off(D0, 2, 1)>(vb), l3 = tr_read<BOFF + v_rd_off(D0, 3, 0)>(vb), h3 = tr_read<BOFF + v_rd_off(D0, 3, 1)>(vb);
;   asm volatile("s_waitcnt lgkmcnt(0)" ::: "memory"); SBAR();
;     ...
;   od = __builtin_amdgcn_mfma_f32_32x32x16_bf16(pa0, PK(l0, h0), od, 0, 0, 0);
;   od = __builtin_amdgcn_mfma_f32_32x32x16_bf16(pa1, PK(l1, h1), od, 0, 0, 0);
;   od = __builtin_amdgcn_mfma_f32_32x32x16_bf16(pa2, PK(l2, h2), od, 0, 0, 0);
;   od = __builtin_amdgcn_mfma_f32_32x32x16_bf16(pa3, PK(l3, h3), od, 0, 0, 0);
;     ...
; }
; template <int BOFF> __device__ __forceinline__ void pv_i(f32x16* o, int vb, bf16x8 pa0, bf16x8 pa1, bf16x8 pa2, bf16x8 pa3) {
;   pv_one_i<0, BOFF>(o[0], vb, pa0, pa1, pa2, pa3); pv_one_i<1, BOFF>(o[1], vb, pa0, pa1, pa2, pa3); pv_one_i<2, BOFF>(o[2], vb, pa0, pa1, pa2, pa3); pv_one_i<3, BOFF>(o[3], vb, pa0, pa1, pa2, pa3);
; }
	v_mfma_f32_32x32x16_bf16 v[0:15], v[100:103], v[184:187], v[0:15]
	ds_read_b64_tr_b16 v[184:185], v206 offset:0x5200
	ds_read_b64_tr_b16 v[186:187], v206 offset:0x5a00
	global_load_dwordx4 v[162:165], v[166:167], off
	s_nop 0
	global_load_dwordx4 v[166:169], v[166:167], off offset:-512
	s_nop 0
	global_load_dwordx4 v[174:177], v[170:171], off
	s_nop 0
	global_load_dwordx4 v[170:173], v[170:171], off offset:-512
	s_waitcnt lgkmcnt(7)
	v_mfma_f32_32x32x16_bf16 v[0:15], v[104:107], v[216:219], v[0:15]
	ds_read_b64_tr_b16 v[216:217], v206 offset:0x6200
	ds_read_b64_tr_b16 v[218:219], v206 offset:0x6a00
	s_waitcnt lgkmcnt(7)
	v_mfma_f32_32x32x16_bf16 v[0:15], v[108:111], v[220:223], v[0:15]
	ds_read_b64_tr_b16 v[220:221], v206 offset:0x7200
	ds_read_b64_tr_b16 v[222:223], v206 offset:0x7a00
	ds_write_b128 v212, v[158:161]
	s_waitcnt lgkmcnt(7)
	v_mfma_f32_32x32x16_bf16 v[16:31], v[96:99], v[180:183], v[16:31]
	ds_read_b64_tr_b16 v[180:181], v206 offset:0x4400
	ds_read_b64_tr_b16 v[182:183], v206 offset:0x4c00
	s_waitcnt lgkmcnt(7)
	v_mfma_f32_32x32x16_bf16 v[16:31], v[100:103], v[184:187], v[16:31]
	ds_read_b64_tr_b16 v[184:185], v206 offset:0x5400
	ds_read_b64_tr_b16 v[186:187], v206 offset:0x5c00
	s_waitcnt lgkmcnt(7)
	v_mfma_f32_32x32x16_bf16 v[16:31], v[104:107], v[216:219], v[16:31]
	ds_read_b64_tr_b16 v[216:217], v206 offset:0x6400
	ds_read_b64_tr_b16 v[218:219], v206 offset:0x6c00
	s_waitcnt lgkmcnt(7)
	v_mfma_f32_32x32x16_bf16 v[16:31], v[108:111], v[220:223], v[16:31]
	ds_read_b64_tr_b16 v[220:221], v206 offset:0x7400
	ds_read_b64_tr_b16 v[222:223], v206 offset:0x7c00
	ds_write_b128 v213, v[150:153]
	s_waitcnt lgkmcnt(7)
	v_mfma_f32_32x32x16_bf16 v[32:47], v[96:99], v[180:183], v[32:47]
	ds_read_b64_tr_b16 v[180:181], v206 offset:0x4600
	ds_read_b64_tr_b16 v[182:183], v206 offset:0x4e00
	s_waitcnt lgkmcnt(7)
	v_mfma_f32_32x32x16_bf16 v[32:47], v[100:103], v[184:187], v[32:47]
	ds_read_b64_tr_b16 v[184:185], v206 offset:0x5600
	ds_read_b64_tr_b16 v[186:187], v206 offset:0x5e00
	s_waitcnt lgkmcnt(7)
	v_mfma_f32_32x32x16_bf16 v[32:47], v[104:107], v[216:219], v[32:47]
	ds_read_b64_tr_b16 v[216:217], v206 offset:0x6600
	ds_read_b64_tr_b16 v[218:219], v206 offset:0x6e00
	s_waitcnt lgkmcnt(7)
	v_mfma_f32_32x32x16_bf16 v[32:47], v[108:111], v[220:223], v[32:47]
	ds_read_b64_tr_b16 v[220:221], v206 offset:0x7600
	ds_read_b64_tr_b16 v[222:223], v206 offset:0x7e00
	ds_write_b128 v214, v[154:157]
	s_waitcnt lgkmcnt(7)
	v_mfma_f32_32x32x16_bf16 v[48:63], v[96:99], v[180:183], v[48:63]
	s_waitcnt vmcnt(4)
	v_exp_f32_e32 v180, v64
	v_exp_f32_e32 v181, v65
	v_exp_f32_e32 v182, v66
	v_exp_f32_e32 v183, v67
	v_exp_f32_e32 v188, v72
	v_exp_f32_e32 v189, v73
	s_waitcnt lgkmcnt(5)
	v_mfma_f32_32x32x16_bf16 v[48:63], v[100:103], v[184:187], v[48:63]
	v_exp_f32_e32 v184, v68
	v_exp_f32_e32 v185, v69
	v_exp_f32_e32 v186, v70
	v_exp_f32_e32 v187, v71
	v_exp_f32_e32 v196, v74
	v_exp_f32_e32 v197, v75
	v_exp_f32_e32 v198, v76
	s_waitcnt lgkmcnt(3)
	v_mfma_f32_32x32x16_bf16 v[48:63], v[104:107], v[216:219], v[48:63]
	v_exp_f32_e32 v199, v77
	v_exp_f32_e32 v216, v78
	v_exp_f32_e32 v217, v79
	s_waitcnt lgkmcnt(0)
	s_barrier
	v_mfma_f32_32x32x16_bf16 v[48:63], v[108:111], v[220:223], v[48:63]
	ds_read_b128 v[64:67], v207
	ds_read_b128 v[68:71], v207 offset:8192
	ds_read_b128 v[146:149], v208
	ds_read_b128 v[150:153], v208 offset:8192
	v_exp_f32_e32 v154, v88
	v_exp_f32_e32 v155, v89
	v_exp_f32_e32 v156, v90
	v_exp_f32_e32 v157, v91
	v_exp_f32_e32 v158, v92
	v_exp_f32_e32 v159, v93
	v_exp_f32_e32 v160, v94
	v_exp_f32_e32 v95, v95
	s_waitcnt lgkmcnt(3)
	v_mfma_f32_32x32x16_bf16 v[96:111], v[64:67], v[142:145], 0
	v_exp_f32_e32 v236, v80
	v_add_f32_e32 v80, 0, v180
	v_add_f32_e32 v80, v181, v80
	v_add_f32_e32 v80, v182, v80
	s_waitcnt lgkmcnt(2)
	v_mfma_f32_32x32x16_bf16 v[64:79], v[68:71], v[142:145], 0
	v_add_f32_e32 v80, v183, v80
	v_add_f32_e32 v80, v184, v80
	v_add_f32_e32 v80, v185, v80
	s_waitcnt lgkmcnt(1)
	v_mfma_f32_32x32x16_bf16 v[96:111], v[146:149], v[138:141], v[96:111]
	v_add_f32_e32 v80, v186, v80
	v_add_f32_e32 v80, v187, v80
	v_add_f32_e32 v80, v188, v80
	s_waitcnt lgkmcnt(0)
	v_mfma_f32_32x32x16_bf16 v[64:79], v[150:153], v[138:141], v[64:79]
	ds_read_b128 v[146:149], v209
	ds_read_b128 v[150:153], v209 offset:8192
	v_add_f32_e32 v80, v189, v80
	v_add_f32_e32 v80, v196, v80
	v_add_f32_e32 v80, v197, v80
	v_add_f32_e32 v80, v198, v80
	v_exp_f32_e32 v237, v81
	s_waitcnt lgkmcnt(1)
	v_mfma_f32_32x32x16_bf16 v[96:111], v[146:149], v[112:115], v[96:111]
	v_add_f32_e32 v80, v199, v80
	v_exp_f32_e32 v238, v82
	v_add_f32_e32 v80, v216, v80
	v_exp_f32_e32 v239, v83
	s_waitcnt lgkmcnt(0)
	v_mfma_f32_32x32x16_bf16 v[64:79], v[150:153], v[112:115], v[64:79]
	ds_read_b128 v[146:149], v210
	ds_read_b128 v[150:153], v210 offset:8192
	v_add_f32_e32 v80, v217, v80
	v_exp_f32_e32 v247, v84
	v_add_f32_e32 v80, v236, v80
	v_exp_f32_e32 v248, v85
	s_waitcnt lgkmcnt(1)
	v_mfma_f32_32x32x16_bf16 v[96:111], v[146:149], v[116:119], v[96:111]
	v_add_f32_e32 v80, v237, v80
	v_exp_f32_e32 v249, v86
	v_add_f32_e32 v80, v238, v80
	v_exp_f32_e32 v252, v87
	s_waitcnt lgkmcnt(0)
	v_mfma_f32_32x32x16_bf16 v[64:79], v[150:153], v[116:119], v[64:79]
	ds_read_b128 v[146:149], v190 offset:0
	ds_read_b128 v[150:153], v190 offset:8192
	v_add_f32_e32 v80, v239, v80
	v_add_f32_e32 v80, v247, v80
	v_add_f32_e32 v80, v248, v80
	v_add_f32_e32 v80, v249, v80
	v_add_f32_e32 v80, v252, v80
	v_add_f32_e32 v80, v154, v80
	s_waitcnt lgkmcnt(1)
	v_mfma_f32_32x32x16_bf16 v[96:111], v[146:149], v[120:123], v[96:111]
	v_add_f32_e32 v80, v155, v80
	v_add_f32_e32 v80, v156, v80
	v_add_f32_e32 v80, v157, v80
	v_add_f32_e32 v80, v158, v80
	v_add_f32_e32 v80, v159, v80
	s_waitcnt lgkmcnt(0)
; #define SBAR() __builtin_amdgcn_sched_barrier(0)
; #define SLOAD(i, k0) do { sr_[i].vs0 = ld8(&Vh[(long)((k0) + sr) * LDK + sc]); sr_[i].vs1 = ld8(&Vh[(long)((k0) + 32 + sr) * LDK + sc]); \
;     sr_[i].ks0 = ld8(&Kh[(long)((k0) + sr) * LDK + sc]); sr_[i].ks1 = ld8(&Kh[(long)((k0) + 32 + sr) * LDK + sc]); } while (0)
; #define SWAIT() asm volatile("s_waitcnt vmcnt(4)" ::: "memory")
; #define NOP_() do { } while (0)
; template <int D0, int BOFF> __device__ __forceinline__ void pv_one_i(f32x16& od, int vb, bf16x8 pa0, bf16x8 pa1, bf16x8 pa2, bf16x8 pa3) {
;   const s16x4 l0 = tr_read<BOFF + v_rd_off(D0, 0, 0)>(vb), h0 = tr_read<BOFF + v_rd_off(D0, 0, 1)>(vb), l1 = tr_read<BOFF + v_rd_off(D0, 1, 0)>(vb), h1 = tr_read<BOFF + v_rd_off(D0, 1, 1)>(vb);
;   const s16x4 l2 = tr_read<BOFF + v_rd_off(D0, 2, 0)>(vb), h2 = tr_read<BOFF + v_rd_off(D0, 2, 1)>(vb), l3 = tr_read<BOFF + v_rd_off(D0, 3, 0)>(vb), h3 = tr_read<BOFF + v_rd_off(D0, 3, 1)>(vb);
;   asm volatile("s_waitcnt lgkmcnt(0)" ::: "memory"); SBAR();
;     ...
;   od = __builtin_amdgcn_mfma_f32_32x32x16_bf16(pa0, PK(l0, h0), od, 0, 0, 0);
;   od = __builtin_amdgcn_mfma_f32_32x32x16_bf16(pa1, PK(l1, h1), od, 0, 0, 0);
;   od = __builtin_amdgcn_mfma_f32_32x32x16_bf16(pa2, PK(l2, h2), od, 0, 0, 0);
;   od = __builtin_amdgcn_mfma_f32_32x32x16_bf16(pa3, PK(l3, h3), od, 0, 0, 0);
;     ...
; }
; template <int BOFF> __device__ __forceinline__ void pv_i(f32x16* o, int vb, bf16x8 pa0, bf16x8 pa1, bf16x8 pa2, bf16x8 pa3) {
;   pv_one_i<0, BOFF>(o[0], vb, pa0, pa1, pa2, pa3); pv_one_i<1, BOFF>(o[1], vb, pa0, pa1, pa2, pa3); pv_one_i<2, BOFF>(o[2], vb, pa0, pa1, pa2, pa3); pv_one_i<3, BOFF>(o[3], vb, pa0, pa1, pa2, pa3);
; }
; template <bool PARTIAL, bool FIXED> ...
;     ...
;   int j = 1;
;   for (; j + 6 < NT; j += 6) {
;     HALF_B(1, 0, SLOAD(1, (j + 2) * KVBLK), do { SWAIT(); SWRITE_I(2, 0); } while (0));
;     HALF_A(2, 1, NOP_(), SLOAD(0, (j + 3) * KVBLK), do { SWAIT(); SWRITE_I(0, 1); } while (0));
;     HALF_B(0, 2, SLOAD(1, (j + 4) * KVBLK), do { SWAIT(); SWRITE_I(1, 0); } while (0));
;     HALF_A(1, 0, NOP_(), SLOAD(0, (j + 5) * KVBLK), do { SWAIT(); SWRITE_I(2, 1); } while (0));
;     HALF_B(2, 1, SLOAD(1, (j + 6) * KVBLK), do { SWAIT(); SWRITE_I(0, 0); } while (0));
;     HALF_A(0, 2, NOP_(), SLOAD(0, (j + 7) * KVBLK), do { SWAIT(); SWRITE_I(1, 1); } while (0));
	v_mfma_f32_32x32x16_bf16 v[64:79], v[150:153], v[120:123], v[64:79]
	ds_read_b128 v[146:149], v191 offset:0
	ds_read_b128 v[150:153], v191 offset:8192
	v_add_f32_e32 v80, v160, v80
	v_add_f32_e32 v80, v95, v80
	v_mov_b32_e32 v81, v80
	s_nop 1
	v_permlane32_swap_b32_e32 v80, v81
	v_add_f32_e32 v80, v80, v81
	s_waitcnt lgkmcnt(1)
	v_mfma_f32_32x32x16_bf16 v[96:111], v[146:149], v[124:127], v[96:111]
	v_add_f32_e32 v215, v128, v80
	v_cvt_pk_bf16_f32 v80, v180, v181
	v_cvt_pk_bf16_f32 v81, v182, v183
	v_cvt_pk_bf16_f32 v82, v184, v185
	v_cvt_pk_bf16_f32 v83, v186, v187
	s_waitcnt lgkmcnt(0)
	v_mfma_f32_32x32x16_bf16 v[64:79], v[150:153], v[124:127], v[64:79]
	ds_read_b128 v[146:149], v192 offset:0
	ds_read_b128 v[150:153], v192 offset:8192
	v_cvt_pk_bf16_f32 v84, v188, v189
	v_cvt_pk_bf16_f32 v85, v196, v197
	v_cvt_pk_bf16_f32 v86, v198, v199
	v_cvt_pk_bf16_f32 v87, v216, v217
	v_cvt_pk_bf16_f32 v88, v236, v237
	v_cvt_pk_bf16_f32 v89, v238, v239
	s_waitcnt lgkmcnt(1)
	v_mfma_f32_32x32x16_bf16 v[96:111], v[146:149], v[130:133], v[96:111]
	v_cvt_pk_bf16_f32 v90, v247, v248
	v_cvt_pk_bf16_f32 v91, v249, v252
	v_cvt_pk_bf16_f32 v92, v154, v155
	v_cvt_pk_bf16_f32 v93, v156, v157
	v_cvt_pk_bf16_f32 v94, v158, v159
	s_waitcnt lgkmcnt(0)
	v_mfma_f32_32x32x16_bf16 v[64:79], v[150:153], v[130:133], v[64:79]
	ds_read_b128 v[146:149], v193 offset:0
	ds_read_b128 v[150:153], v193 offset:8192
	ds_read_b64_tr_b16 v[180:181], v206 offset:0x8000
	ds_read_b64_tr_b16 v[182:183], v206 offset:0x8800
	ds_read_b64_tr_b16 v[184:185], v206 offset:0x9000
	ds_read_b64_tr_b16 v[186:187], v206 offset:0x9800
	ds_read_b64_tr_b16 v[216:217], v206 offset:0xa000
	ds_read_b64_tr_b16 v[218:219], v206 offset:0xa800
	ds_read_b64_tr_b16 v[220:221], v206 offset:0xb000
	ds_read_b64_tr_b16 v[222:223], v206 offset:0xb800
	v_cvt_pk_bf16_f32 v95, v160, v95
	s_nop 0
	v_permlane32_swap_b32_e32 v80, v82
	v_permlane32_swap_b32_e32 v81, v83
	v_permlane32_swap_b32_e32 v84, v86
	v_permlane32_swap_b32_e32 v85, v87
	s_waitcnt lgkmcnt(9)
	v_mfma_f32_32x32x16_bf16 v[96:111], v[146:149], v[134:137], v[96:111]
	v_permlane32_swap_b32_e32 v88, v90
	v_permlane32_swap_b32_e32 v89, v91
	v_permlane32_swap_b32_e32 v92, v94
	v_permlane32_swap_b32_e32 v93, v95
	s_waitcnt lgkmcnt(8)
	v_mfma_f32_32x32x16_bf16 v[64:79], v[150:153], v[134:137], v[64:79]
	s_waitcnt vmcnt(0)
	ds_write_b128 v211, v[162:165] offset:16384
	s_nop 0
	s_waitcnt lgkmcnt(7)
	v_mfma_f32_32x32x16_bf16 v[0:15], v[80:83], v[180:183], v[0:15]
	ds_read_b64_tr_b16 v[180:181], v206 offset:0x8200
	ds_read_b64_tr_b16 v[182:183], v206 offset:0x8a00
	v_add_co_u32_e32 v150, vcc, s58, v178
	s_nop 1
	v_addc_co_u32_e32 v151, vcc, -1, v179, vcc
	s_waitcnt lgkmcnt(7)
	v_mfma_f32_32x32x16_bf16 v[0:15], v[84:87], v[184:187], v[0:15]
	ds_read_b64_tr_b16 v[184:185], v206 offset:0x9200
	ds_read_b64_tr_b16 v[186:187], v206 offset:0x9a00
	global_load_dwordx4 v[146:149], v[150:151], off
	global_load_dwordx4 v[154:157], v[150:151], off offset:-512
	s_nop 0
	global_load_dwordx4 v[150:153], v[178:179], off
	global_load_dwordx4 v[158:161], v[178:179], off offset:-512
	s_waitcnt lgkmcnt(7)
	v_mfma_f32_32x32x16_bf16 v[0:15], v[88:91], v[216:219], v[0:15]
	ds_read_b64_tr_b16 v[216:217], v206 offset:0xa200
	ds_read_b64_tr_b16 v[218:219], v206 offset:0xaa00
	s_waitcnt lgkmcnt(7)
	v_mfma_f32_32x32x16_bf16 v[0:15], v[92:95], v[220:223], v[0:15]
	ds_read_b64_tr_b16 v[220:221], v206 offset:0xb200
	ds_read_b64_tr_b16 v[222:223], v206 offset:0xba00
	ds_write_b128 v212, v[174:177] offset:16384
	s_waitcnt lgkmcnt(7)
	v_mfma_f32_32x32x16_bf16 v[16:31], v[80:83], v[180:183], v[16:31]
	ds_read_b64_tr_b16 v[180:181], v206 offset:0x8400
	ds_read_b64_tr_b16 v[182:183], v206 offset:0x8c00
	s_waitcnt lgkmcnt(7)
	v_mfma_f32_32x32x16_bf16 v[16:31], v[84:87], v[184:187], v[16:31]
	ds_read_b64_tr_b16 v[184:185], v206 offset:0x9400
	ds_read_b64_tr_b16 v[186:187], v206 offset:0x9c00
	s_waitcnt lgkmcnt(7)
	v_mfma_f32_32x32x16_bf16 v[16:31], v[88:91], v[216:219], v[16:31]
	ds_read_b64_tr_b16 v[216:217], v206 offset:0xa400
	ds_read_b64_tr_b16 v[218:219], v206 offset:0xac00
	s_waitcnt lgkmcnt(7)
	v_mfma_f32_32x32x16_bf16 v[16:31], v[92:95], v[220:223], v[16:31]
	ds_read_b64_tr_b16 v[220:221], v206 offset:0xb400
	ds_read_b64_tr_b16 v[222:223], v206 offset:0xbc00
	ds_write_b128 v213, v[166:169] offset:16384
	s_waitcnt lgkmcnt(7)
	v_mfma_f32_32x32x16_bf16 v[32:47], v[80:83], v[180:183], v[32:47]
	ds_read_b64_tr_b16 v[180:181], v206 offset:0x8600
	ds_read_b64_tr_b16 v[182:183], v206 offset:0x8e00
	s_waitcnt lgkmcnt(7)
	v_mfma_f32_32x32x16_bf16 v[32:47], v[84:87], v[184:187], v[32:47]
	ds_read_b64_tr_b16 v[184:185], v206 offset:0x9600
	ds_read_b64_tr_b16 v[186:187], v206 offset:0x9e00
	s_waitcnt lgkmcnt(7)
	v_mfma_f32_32x32x16_bf16 v[32:47], v[88:91], v[216:219], v[32:47]
	ds_read_b64_tr_b16 v[216:217], v206 offset:0xa600
	ds_read_b64_tr_b16 v[218:219], v206 offset:0xae00
	s_waitcnt lgkmcnt(7)
	v_mfma_f32_32x32x16_bf16 v[32:47], v[92:95], v[220:223], v[32:47]
	ds_read_b64_tr_b16 v[220:221], v206 offset:0xb600
	ds_read_b64_tr_b16 v[222:223], v206 offset:0xbe00
	ds_write_b128 v214, v[170:173] offset:16384
	s_waitcnt lgkmcnt(7)
	v_mfma_f32_32x32x16_bf16 v[48:63], v[80:83], v[180:183], v[48:63]
	v_exp_f32_e32 v229, v96
	v_exp_f32_e32 v243, v97
	v_exp_f32_e32 v244, v98
	v_exp_f32_e32 v246, v99
	v_exp_f32_e32 v242, v100
	v_exp_f32_e32 v245, v101
	v_exp_f32_e32 v227, v102
	s_waitcnt lgkmcnt(5)
	v_mfma_f32_32x32x16_bf16 v[48:63], v[84:87], v[184:187], v[48:63]
	v_exp_f32_e32 v228, v103
	v_exp_f32_e32 v226, v105
	v_exp_f32_e32 v224, v106
	v_exp_f32_e32 v225, v107
	s_waitcnt vmcnt(4)
	s_add_i32 s28, s28, 6
	v_lshl_add_u64 v[178:179], v[178:179], 0, s[60:61]
	s_waitcnt lgkmcnt(3)
	v_mfma_f32_32x32x16_bf16 v[48:63], v[88:91], v[216:219], v[48:63]
	v_exp_f32_e32 v219, v110
	s_cmpk_lt_u32 s28, 0x75
	s_waitcnt lgkmcnt(1)
	v_mfma_f32_32x32x16_bf16 v[48:63], v[92:95], v[220:223], v[48:63]
	v_exp_f32_e32 v223, v104
	v_exp_f32_e32 v220, v108
	v_exp_f32_e32 v222, v109
	v_exp_f32_e32 v221, v111
	s_cbranch_scc1 .LBB0_352
; #define NOP_() do { } while (0)
; __device__ __forceinline__ void finishSM(f32x16& p0, f32x16& p1, float alpha, float& l_reg, bf16x8& pa0, bf16x8& pa1, bf16x8& pa2, bf16x8& pa3) {
;   for (int r = 0; r < 16; ++r) p1[r] = __builtin_amdgcn_exp2f(p1[r]);
;   float ps = 0; for (int r = 0; r < 16; ++r) ps += p0[r]; for (int r = 0; r < 16; ++r) ps += p1[r];
;   { auto rr = __builtin_amdgcn_permlane32_swap(__float_as_uint(ps), __float_as_uint(ps), false, false);
;     ps = __uint_as_float(rr[0]) + __uint_as_float(rr[1]); }
;   l_reg = l_reg * alpha + ps;
;     ...
;   PK4(p0, 0, pa0); PK4(p0, 8, pa1); PK4(p1, 0, pa2); PK4(p1, 8, pa3);
;     ...
; }
; __device__ __forceinline__ void qkt(f32x16& p0, f32x16& p1, const bf16* Ks, const bf16x8* qr, int r32, int hi) {
;   p0 = f32x16{}; p1 = f32x16{};
;   for (int d0 = 0; d0 < 8; ++d0) { int cb = (d0 * 16 + hi * 8) * 2;
;     bf16x8 b0 = *reinterpret_cast<const bf16x8*>((const char*)Ks + KSWZ(r32, cb));
;     bf16x8 b1 = *reinterpret_cast<const bf16x8*>((const char*)Ks + KSWZ(32 + r32, cb));
;     p0 = __builtin_amdgcn_mfma_f32_32x32x16_bf16(b0, qr[d0], p0, 0, 0, 0);
;     p1 = __builtin_amdgcn_mfma_f32_32x32x16_bf16(b1, qr[d0], p1, 0, 0, 0); }
; }
; __device__ __forceinline__ int v_st(int k, int c) { const int kk = (k & ~0xC) | ((k & 4) << 1) | ((k & 8) >> 1); return ((kk >> 3) * 4 + (c >> 5)) * 512 + ((kk & 7) * 32 + (c & 31)) * 2; }
; __device__ __forceinline__ int v_rd_base(int lane) { return ((lane & 3) << 3) | (((lane >> 2) & 3) << 6) | (((lane >> 4) & 1) << 5) | (((lane >> 5) & 1) << 8); }
; template <int OFF> __device__ __forceinline__ s16x4 tr_read(int vb) {
;   s16x4 r; asm volatile("ds_read_b64_tr_b16 %0, %1 offset:%2" : "=&v"(r) : "v"(vb), "i"(OFF) : "memory"); return r;
; }
; template <int D0> __device__ __forceinline__ void pv_one(f32x16& od, int vb, bf16x8 pa0, bf16x8 pa1, bf16x8 pa2, bf16x8 pa3) {
;   const s16x4 l0 = tr_read<v_rd_off(D0, 0, 0)>(vb), h0 = tr_read<v_rd_off(D0, 0, 1)>(vb), l1 = tr_read<v_rd_off(D0, 1, 0)>(vb), h1 = tr_read<v_rd_off(D0, 1, 1)>(vb);
; template <bool PARTIAL, bool FIXED> ...
;     ...
;   if constexpr (!PARTIAL) { const int i1 = tid & 255;
;     warm0 = *(const unsigned*)(Qb_n + (long)(tid >> 1) * LDQ + (tid & 1) * 64);
;     warm1 = *(const unsigned*)((tid < 256 ? Kh_n : Vh_n) + (long)(i1 >> 1) * LDK + (i1 & 1) * 64); }
;   HALF_B(1, 0, NOP_(), SWRITE_I(2, 0));
	v_mov_b32_e32 v252, 0x7fc00000
	v_readlane_b32 s8, v255, 42
	v_readlane_b32 s9, v255, 43
	s_add_u32 s2, s8, s6
	s_addc_u32 s3, s9, s7
	s_lshl_b32 s4, s65, 1
	s_add_u32 s2, s2, s4
	s_addc_u32 s3, s3, 0
	v_ashrrev_i32_e32 v82, 1, v195
	v_mov_b64_e32 v[80:81], s[2:3]
	v_mad_i64_i32 v[80:81], s[2:3], v82, s17, v[80:81]
	v_lshlrev_b32_e32 v82, 7, v195
	v_and_b32_e32 v128, 0x80, v82
	v_lshl_add_u64 v[80:81], v[80:81], 0, v[128:129]
	s_add_u32 s4, s8, s64
	global_load_dword v216, v[80:81], off
	v_cmp_gt_i32_e32 vcc, s14, v195
	v_mov_b32_e32 v80, 0xa00
	v_mov_b32_e32 v81, 0x800
	s_addc_u32 s5, s9, s57
	v_cndmask_b32_e32 v80, v80, v81, vcc
	v_mov_b32_e32 v81, v129
	v_bfe_u32 v82, v195, 1, 7
	v_lshl_add_u64 v[80:81], s[4:5], 0, v[80:81]
	s_lshl_b32 s46, s56, 1
	v_mul_u32_u24_e32 v82, 0x600, v82
	v_lshl_add_u64 v[80:81], v[80:81], 0, s[46:47]
	v_lshlrev_b32_e32 v82, 1, v82
	v_mov_b32_e32 v83, v129
	v_lshl_add_u64 v[80:81], v[80:81], 0, v[82:83]
	v_lshl_add_u64 v[80:81], v[80:81], 0, v[128:129]
	global_load_dword v217, v[80:81], off
	v_and_b32_e32 v247, 0x3fffffc0, v195
	s_waitcnt lgkmcnt(0)
	s_barrier
	ds_read_b128 v[80:83], v207 offset:16384
	ds_read_b128 v[96:99], v207 offset:24576
	ds_read_b128 v[100:103], v208 offset:16384
	ds_read_b128 v[170:173], v208 offset:24576
	v_exp_f32_e32 v104, v68
	v_exp_f32_e32 v105, v69
	s_waitcnt lgkmcnt(3)
	v_mfma_f32_32x32x16_bf16 v[80:95], v[80:83], v[142:145], 0
	v_exp_f32_e32 v106, v70
	v_exp_f32_e32 v107, v71
	v_exp_f32_e32 v108, v72
	v_exp_f32_e32 v109, v73
	v_exp_f32_e32 v110, v74
	v_exp_f32_e32 v111, v75
	v_exp_f32_e32 v196, v76
	s_waitcnt lgkmcnt(1)
	v_mfma_f32_32x32x16_bf16 v[80:95], v[100:103], v[138:141], v[80:95]
	ds_read_b128 v[100:103], v209 offset:16384
	ds_read_b128 v[162:165], v209 offset:24576
	v_exp_f32_e32 v197, v77
	v_exp_f32_e32 v198, v78
	v_exp_f32_e32 v79, v79
	s_waitcnt lgkmcnt(1)
	v_mfma_f32_32x32x16_bf16 v[80:95], v[100:103], v[112:115], v[80:95]
	ds_read_b128 v[100:103], v210 offset:16384
	ds_read_b128 v[166:169], v210 offset:24576
	s_waitcnt lgkmcnt(1)
	v_mfma_f32_32x32x16_bf16 v[80:95], v[100:103], v[116:119], v[80:95]
	ds_read_b128 v[100:103], v190 offset:16384
	ds_read_b128 v[174:177], v190 offset:24576
	s_waitcnt lgkmcnt(1)
	v_mfma_f32_32x32x16_bf16 v[80:95], v[100:103], v[120:123], v[80:95]
	ds_read_b128 v[100:103], v191 offset:16384
	ds_read_b128 v[178:181], v191 offset:24576
	s_waitcnt lgkmcnt(1)
	v_mfma_f32_32x32x16_bf16 v[80:95], v[100:103], v[124:127], v[80:95]
	ds_read_b128 v[100:103], v192 offset:16384
	ds_read_b128 v[182:185], v192 offset:24576
	s_waitcnt lgkmcnt(1)
	v_mfma_f32_32x32x16_bf16 v[80:95], v[100:103], v[130:133], v[80:95]
	ds_read_b128 v[100:103], v193 offset:16384
	ds_read_b128 v[186:189], v193 offset:24576
	s_waitcnt lgkmcnt(1)
	v_mfma_f32_32x32x16_bf16 v[80:95], v[100:103], v[134:137], v[80:95]
	v_exp_f32_e32 v100, v64
	v_add_f32_e32 v64, 0, v229
	v_add_f32_e32 v64, v243, v64
	v_add_f32_e32 v64, v244, v64
	v_add_f32_e32 v64, v246, v64
	v_add_f32_e32 v64, v242, v64
	v_add_f32_e32 v64, v245, v64
	v_add_f32_e32 v64, v227, v64
	v_add_f32_e32 v64, v228, v64
	v_add_f32_e32 v64, v223, v64
	v_add_f32_e32 v64, v226, v64
	v_add_f32_e32 v64, v224, v64
	v_add_f32_e32 v64, v225, v64
	v_add_f32_e32 v64, v220, v64
	v_exp_f32_e32 v101, v65
	v_add_f32_e32 v64, v222, v64
	v_exp_f32_e32 v102, v66
	v_add_f32_e32 v64, v219, v64
	v_exp_f32_e32 v103, v67
	v_add_f32_e32 v64, v221, v64
	v_add_f32_e32 v64, v100, v64
	v_add_f32_e32 v64, v101, v64
	v_add_f32_e32 v64, v102, v64
	v_add_f32_e32 v64, v103, v64
	v_add_f32_e32 v64, v104, v64
	v_add_f32_e32 v64, v105, v64
	v_add_f32_e32 v64, v106, v64
	v_add_f32_e32 v64, v107, v64
	v_add_f32_e32 v64, v108, v64
	v_add_f32_e32 v64, v109, v64
	v_add_f32_e32 v64, v110, v64
	v_add_f32_e32 v64, v111, v64
	v_add_f32_e32 v64, v196, v64
	v_add_f32_e32 v64, v197, v64
	v_add_f32_e32 v64, v198, v64
	v_add_f32_e32 v128, v79, v64
	v_mov_b32_e32 v218, v128
	s_nop 1
	v_permlane32_swap_b32_e32 v128, v218
	v_cvt_pk_bf16_f32 v64, v229, v243
	v_cvt_pk_bf16_f32 v65, v244, v246
	v_cvt_pk_bf16_f32 v66, v242, v245
	v_cvt_pk_bf16_f32 v67, v227, v228
	v_cvt_pk_bf16_f32 v68, v223, v226
	v_cvt_pk_bf16_f32 v69, v224, v225
	v_cvt_pk_bf16_f32 v70, v220, v222
	v_cvt_pk_bf16_f32 v71, v219, v221
	v_cvt_pk_bf16_f32 v72, v100, v101
	v_cvt_pk_bf16_f32 v73, v102, v103
	v_cvt_pk_bf16_f32 v74, v104, v105
	v_cvt_pk_bf16_f32 v75, v106, v107
	v_cvt_pk_bf16_f32 v76, v108, v109
	v_cvt_pk_bf16_f32 v77, v110, v111
	v_cvt_pk_bf16_f32 v78, v196, v197
	v_cvt_pk_bf16_f32 v79, v198, v79
	s_nop 0
	v_permlane32_swap_b32_e32 v64, v66
	v_permlane32_swap_b32_e32 v65, v67
	v_permlane32_swap_b32_e32 v68, v70
	v_permlane32_swap_b32_e32 v69, v71
	v_permlane32_swap_b32_e32 v72, v74
	v_permlane32_swap_b32_e32 v73, v75
	v_permlane32_swap_b32_e32 v76, v78
	v_permlane32_swap_b32_e32 v77, v79
	ds_read_b64_tr_b16 v[100:101], v206 offset:0
	ds_read_b64_tr_b16 v[102:103], v206 offset:0x800
	ds_read_b64_tr_b16 v[104:105], v206 offset:0x1000
	ds_read_b64_tr_b16 v[106:107], v206 offset:0x1800
	ds_read_b64_tr_b16 v[108:109], v206 offset:0x2000
	ds_read_b64_tr_b16 v[110:111], v206 offset:0x2800
	ds_read_b64_tr_b16 v[220:221], v206 offset:0x3000
	ds_read_b64_tr_b16 v[222:223], v206 offset:0x3800
	s_waitcnt lgkmcnt(0)
	s_nop 0
	v_mfma_f32_32x32x16_bf16 v[0:15], v[64:67], v[100:103], v[0:15]
	ds_read_b64_tr_b16 v[100:101], v206 offset:0x200
	ds_read_b64_tr_b16 v[102:103], v206 offset:0xa00
	v_mfma_f32_32x32x16_bf16 v[0:15], v[68:71], v[104:107], v[0:15]
	ds_read_b64_tr_b16 v[104:105], v206 offset:0x1200
	ds_read_b64_tr_b16 v[106:107], v206 offset:0x1a00
	v_mfma_f32_32x32x16_bf16 v[0:15], v[72:75], v[108:111], v[0:15]
	ds_read_b64_tr_b16 v[108:109], v206 offset:0x2200
	ds_read_b64_tr_b16 v[110:111], v206 offset:0x2a00
	v_mfma_f32_32x32x16_bf16 v[0:15], v[76:79], v[220:223], v[0:15]
	ds_read_b64_tr_b16 v[220:221], v206 offset:0x3200
	ds_read_b64_tr_b16 v[222:223], v206 offset:0x3a00
	s_waitcnt lgkmcnt(0)
; #define SBAR() __builtin_amdgcn_sched_barrier(0)
; #define SWRITE_I(B, i) do { LDSV(wv0 + (B) * 16384) = sr_[i].vs0; LDSV(wv1 + (B) * 16384) = sr_[i].vs1; LDSV(wk0 + (B) * 16384) = sr_[i].ks0; LDSV(wk1 + (B) * 16384) = sr_[i].ks1; } while (0)
; #define NOP_() do { } while (0)
; template <int BOFF> __device__ __forceinline__ void qkt_i(f32x16& p0, f32x16& p1, const int (&kb)[4], const bf16x8* qr) {
;   p0 = f32x16{}; p1 = f32x16{};
; #pragma unroll
;   for (int d0 = 0; d0 < 8; ++d0) { const int off = BOFF + (d0 >> 2) * 128;
;     const bf16x8 b0 = LDSV(kb[d0 & 3] + off), b1 = LDSV(kb[d0 & 3] + off + 8192);
;     p0 = __builtin_amdgcn_mfma_f32_32x32x16_bf16(b0, qr[d0], p0, 0, 0, 0);
;     p1 = __builtin_amdgcn_mfma_f32_32x32x16_bf16(b1, qr[d0], p1, 0, 0, 0); }
; }
; template <int D0, int BOFF> __device__ __forceinline__ void pv_one_i(f32x16& od, int vb, bf16x8 pa0, bf16x8 pa1, bf16x8 pa2, bf16x8 pa3) {
;   const s16x4 l0 = tr_read<BOFF + v_rd_off(D0, 0, 0)>(vb), h0 = tr_read<BOFF + v_rd_off(D0, 0, 1)>(vb), l1 = tr_read<BOFF + v_rd_off(D0, 1, 0)>(vb), h1 = tr_read<BOFF + v_rd_off(D0, 1, 1)>(vb);
;   const s16x4 l2 = tr_read<BOFF + v_rd_off(D0, 2, 0)>(vb), h2 = tr_read<BOFF + v_rd_off(D0, 2, 1)>(vb), l3 = tr_read<BOFF + v_rd_off(D0, 3, 0)>(vb), h3 = tr_read<BOFF + v_rd_off(D0, 3, 1)>(vb);
;   asm volatile("s_waitcnt lgkmcnt(0)" ::: "memory"); SBAR();
;     ...
;   od = __builtin_amdgcn_mfma_f32_32x32x16_bf16(pa0, PK(l0, h0), od, 0, 0, 0);
;   od = __builtin_amdgcn_mfma_f32_32x32x16_bf16(pa1, PK(l1, h1), od, 0, 0, 0);
;   od = __builtin_amdgcn_mfma_f32_32x32x16_bf16(pa2, PK(l2, h2), od, 0, 0, 0);
;   od = __builtin_amdgcn_mfma_f32_32x32x16_bf16(pa3, PK(l3, h3), od, 0, 0, 0);
;     ...
; }
; template <int BOFF> __device__ __forceinline__ void pv_i(f32x16* o, int vb, bf16x8 pa0, bf16x8 pa1, bf16x8 pa2, bf16x8 pa3) {
;   pv_one_i<0, BOFF>(o[0], vb, pa0, pa1, pa2, pa3); pv_one_i<1, BOFF>(o[1], vb, pa0, pa1, pa2, pa3); pv_one_i<2, BOFF>(o[2], vb, pa0, pa1, pa2, pa3); pv_one_i<3, BOFF>(o[3], vb, pa0, pa1, pa2, pa3);
; }
; template <bool PARTIAL, bool FIXED> ...
;     ...
;   HALF_B(1, 0, NOP_(), SWRITE_I(2, 0));
;   HALF_A(2, 1, do { if (mask_last) { asm volatile("; masked tail tile" ::: "memory"); const float NEG = -INFINITY; \
;       _Pragma("unroll") for (int r = 8; r < 16; ++r) pA0[r] = NEG; _Pragma("unroll") for (int r = 0; r < 16; ++r) pA1[r] = NEG; } } while (0), NOP_(), NOP_());
	v_mfma_f32_32x32x16_bf16 v[16:31], v[64:67], v[100:103], v[16:31]
	ds_read_b64_tr_b16 v[100:101], v206 offset:0x400
	ds_read_b64_tr_b16 v[102:103], v206 offset:0xc00
	v_mfma_f32_32x32x16_bf16 v[16:31], v[68:71], v[104:107], v[16:31]
	ds_read_b64_tr_b16 v[104:105], v206 offset:0x1400
	ds_read_b64_tr_b16 v[106:107], v206 offset:0x1c00
	v_mfma_f32_32x32x16_bf16 v[16:31], v[72:75], v[108:111], v[16:31]
	ds_read_b64_tr_b16 v[108:109], v206 offset:0x2400
	ds_read_b64_tr_b16 v[110:111], v206 offset:0x2c00
	v_mfma_f32_32x32x16_bf16 v[16:31], v[76:79], v[220:223], v[16:31]
	ds_read_b64_tr_b16 v[220:221], v206 offset:0x3400
	ds_read_b64_tr_b16 v[222:223], v206 offset:0x3c00
	s_waitcnt lgkmcnt(0)
	v_mfma_f32_32x32x16_bf16 v[32:47], v[64:67], v[100:103], v[32:47]
	ds_read_b64_tr_b16 v[100:101], v206 offset:0x600
	ds_read_b64_tr_b16 v[102:103], v206 offset:0xe00
	v_mfma_f32_32x32x16_bf16 v[32:47], v[68:71], v[104:107], v[32:47]
	ds_read_b64_tr_b16 v[104:105], v206 offset:0x1600
	ds_read_b64_tr_b16 v[106:107], v206 offset:0x1e00
	v_mfma_f32_32x32x16_bf16 v[32:47], v[72:75], v[108:111], v[32:47]
	ds_read_b64_tr_b16 v[108:109], v206 offset:0x2600
	ds_read_b64_tr_b16 v[110:111], v206 offset:0x2e00
	v_mfma_f32_32x32x16_bf16 v[32:47], v[76:79], v[220:223], v[32:47]
	ds_read_b64_tr_b16 v[220:221], v206 offset:0x3600
	ds_read_b64_tr_b16 v[222:223], v206 offset:0x3e00
	s_waitcnt lgkmcnt(0)
	v_mfma_f32_32x32x16_bf16 v[48:63], v[64:67], v[100:103], v[48:63]
	s_waitcnt vmcnt(5)
	ds_write_b128 v211, v[146:149] offset:32768
	s_waitcnt vmcnt(3)
	ds_write_b128 v212, v[150:153] offset:32768
	ds_write_b128 v213, v[154:157] offset:32768
	s_waitcnt vmcnt(2)
	ds_write_b128 v214, v[158:161] offset:32768
	s_waitcnt lgkmcnt(0)
	s_barrier
	v_mfma_f32_32x32x16_bf16 v[48:63], v[68:71], v[104:107], v[48:63]
	v_mfma_f32_32x32x16_bf16 v[48:63], v[72:75], v[108:111], v[48:63]
	v_mfma_f32_32x32x16_bf16 v[48:63], v[76:79], v[220:223], v[48:63]
	ds_read_b128 v[64:67], v207 offset:32768
	ds_read_b128 v[100:103], v208 offset:32768
	s_add_i32 s2, 0, 0x18000
	s_waitcnt lgkmcnt(1)
	v_mfma_f32_32x32x16_bf16 v[64:79], v[64:67], v[142:145], 0
	s_waitcnt lgkmcnt(0)
	v_mfma_f32_32x32x16_bf16 v[64:79], v[100:103], v[138:141], v[64:79]
	ds_read_b128 v[100:103], v209 offset:32768
	s_waitcnt lgkmcnt(0)
	v_mfma_f32_32x32x16_bf16 v[64:79], v[100:103], v[112:115], v[64:79]
	ds_read_b128 v[100:103], v210 offset:32768
	s_waitcnt lgkmcnt(0)
	v_mfma_f32_32x32x16_bf16 v[64:79], v[100:103], v[116:119], v[64:79]
	ds_read_b128 v[100:103], v190 offset:32768
	s_waitcnt lgkmcnt(0)
	v_mfma_f32_32x32x16_bf16 v[64:79], v[100:103], v[120:123], v[64:79]
	ds_read_b128 v[100:103], v191 offset:32768
	s_waitcnt lgkmcnt(0)
	v_mfma_f32_32x32x16_bf16 v[64:79], v[100:103], v[124:127], v[64:79]
	ds_read_b128 v[100:103], v192 offset:32768
	s_waitcnt lgkmcnt(0)
	v_mfma_f32_32x32x16_bf16 v[64:79], v[100:103], v[130:133], v[64:79]
	ds_read_b128 v[100:103], v193 offset:32768
	s_waitcnt lgkmcnt(0)
	v_and_b32_e32 v190, 63, v195
	v_lshlrev_b32_e32 v191, 4, v195
	v_and_b32_e32 v192, 31, v195
	v_bfe_u32 v193, v195, 5, 1
	v_mfma_f32_32x32x16_bf16 v[64:79], v[100:103], v[134:137], v[64:79]
	v_mfma_f32_32x32x16_bf16 v[96:111], v[96:99], v[142:145], 0
	s_nop 10
	v_exp_f32_e32 v72, v80
	v_exp_f32_e32 v80, v81
	v_exp_f32_e32 v73, v82
	v_exp_f32_e32 v81, v83
	v_exp_f32_e32 v74, v84
	v_add_f32_e32 v84, 0, v72
	v_exp_f32_e32 v82, v85
	v_mfma_f32_32x32x16_bf16 v[96:111], v[170:173], v[138:141], v[96:111]
	v_add_f32_e32 v84, v80, v84
	v_exp_f32_e32 v75, v86
	v_add_f32_e32 v84, v73, v84
	v_exp_f32_e32 v83, v87
	v_add_f32_e32 v84, v81, v84
	v_exp_f32_e32 v76, v88
	v_add_f32_e32 v84, v74, v84
	v_mfma_f32_32x32x16_bf16 v[96:111], v[162:165], v[112:115], v[96:111]
	v_exp_f32_e32 v85, v89
	v_add_f32_e32 v84, v82, v84
	v_exp_f32_e32 v77, v90
	v_add_f32_e32 v84, v75, v84
	v_exp_f32_e32 v87, v91
	v_add_f32_e32 v84, v83, v84
	v_exp_f32_e32 v78, v92
	v_mfma_f32_32x32x16_bf16 v[96:111], v[166:169], v[116:119], v[96:111]
	v_add_f32_e32 v84, v76, v84
	v_exp_f32_e32 v89, v93
	v_add_f32_e32 v84, v85, v84
	v_exp_f32_e32 v79, v94
	v_add_f32_e32 v84, v77, v84
	v_exp_f32_e32 v90, v95
	v_add_f32_e32 v84, v87, v84
	v_mfma_f32_32x32x16_bf16 v[96:111], v[174:177], v[120:123], v[96:111]
	v_add_f32_e32 v84, v78, v84
	v_add_f32_e32 v84, v89, v84
	v_add_f32_e32 v84, v79, v84
	v_add_f32_e32 v84, v90, v84
	v_lshl_add_u32 v88, v247, 2, s2
	v_cvt_pk_bf16_f32 v72, v72, v80
	v_cvt_pk_bf16_f32 v73, v73, v81
	v_mfma_f32_32x32x16_bf16 v[96:111], v[178:181], v[124:127], v[96:111]
	v_cvt_pk_bf16_f32 v74, v74, v82
	v_cvt_pk_bf16_f32 v75, v75, v83
	v_cvt_pk_bf16_f32 v76, v76, v85
	v_cvt_pk_bf16_f32 v77, v77, v87
	v_cvt_pk_bf16_f32 v78, v78, v89
	v_cvt_pk_bf16_f32 v79, v79, v90
	s_nop 0
	v_permlane32_swap_b32_e32 v72, v74
	v_mfma_f32_32x32x16_bf16 v[96:111], v[182:185], v[130:133], v[96:111]
	v_permlane32_swap_b32_e32 v73, v75
	v_permlane32_swap_b32_e32 v76, v78
	v_permlane32_swap_b32_e32 v77, v79
	v_mfma_f32_32x32x16_bf16 v[96:111], v[186:189], v[134:137], v[96:111]
	s_nop 11
	v_exp_f32_e32 v91, v96
	v_exp_f32_e32 v92, v97
	v_exp_f32_e32 v93, v98
	v_exp_f32_e32 v94, v99
	v_exp_f32_e32 v95, v100
	v_add_f32_e32 v84, v84, v91
	v_exp_f32_e32 v96, v101
	v_add_f32_e32 v84, v92, v84
	v_exp_f32_e32 v97, v102
	v_add_f32_e32 v84, v93, v84
	v_exp_f32_e32 v98, v103
	v_add_f32_e32 v84, v94, v84
	v_exp_f32_e32 v99, v104
	v_add_f32_e32 v84, v95, v84
	v_exp_f32_e32 v100, v105
	v_add_f32_e32 v84, v96, v84
	v_exp_f32_e32 v101, v106
	v_add_f32_e32 v84, v97, v84
	v_exp_f32_e32 v102, v107
	v_add_f32_e32 v84, v98, v84
	v_exp_f32_e32 v103, v108
	v_add_f32_e32 v84, v99, v84
	v_exp_f32_e32 v104, v109
	v_add_f32_e32 v84, v100, v84
	v_exp_f32_e32 v105, v110
	v_add_f32_e32 v84, v101, v84
	v_exp_f32_e32 v106, v111
	v_add_f32_e32 v84, v102, v84
	v_add_f32_e32 v84, v103, v84
	v_add_f32_e32 v84, v104, v84
	v_add_f32_e32 v84, v105, v84
	v_add_f32_e32 v84, v106, v84
	v_mov_b32_e32 v86, v84
	s_nop 1
	v_permlane32_swap_b32_e32 v84, v86
	v_cvt_pk_bf16_f32 v80, v91, v92
	v_cvt_pk_bf16_f32 v81, v93, v94
	v_cvt_pk_bf16_f32 v82, v95, v96
	v_cvt_pk_bf16_f32 v83, v97, v98
	v_cvt_pk_bf16_f32 v90, v99, v100
	v_cvt_pk_bf16_f32 v91, v101, v102
	v_cvt_pk_bf16_f32 v92, v103, v104
	v_cvt_pk_bf16_f32 v93, v105, v106
	s_nop 0
	v_permlane32_swap_b32_e32 v80, v82
	v_permlane32_swap_b32_e32 v81, v83
	v_permlane32_swap_b32_e32 v90, v92
	v_permlane32_swap_b32_e32 v91, v93
	ds_read_b64_tr_b16 v[94:95], v206 offset:0x4000
	ds_read_b64_tr_b16 v[96:97], v206 offset:0x4800
	ds_read_b64_tr_b16 v[98:99], v206 offset:0x5000
	ds_read_b64_tr_b16 v[100:101], v206 offset:0x5800
	ds_read_b64_tr_b16 v[102:103], v206 offset:0x6000
	ds_read_b64_tr_b16 v[104:105], v206 offset:0x6800
	ds_read_b64_tr_b16 v[106:107], v206 offset:0x7000
	ds_read_b64_tr_b16 v[108:109], v206 offset:0x7800
	s_waitcnt lgkmcnt(0)
; #define SBAR() __builtin_amdgcn_sched_barrier(0)
; __device__ __forceinline__ int crow(int r, int hi) { return (r & 3) + 8 * (r >> 2) + 4 * hi; }
; #define NOP_() do { } while (0)
; template <bool PARTIAL, bool FIXED> ...
;     ...
;   HALF_A(2, 1, do { if (mask_last) { asm volatile("; masked tail tile" ::: "memory"); const float NEG = -INFINITY; \
;       _Pragma("unroll") for (int r = 8; r < 16; ++r) pA0[r] = NEG; _Pragma("unroll") for (int r = 0; r < 16; ++r) pA1[r] = NEG; } } while (0), NOP_(), NOP_());
;     ...
;   SBAR(); finishSM(pA0, pA1, alA, l_reg, pa0, pa1, pa2, pa3); SBAR();
;   pv_i<2 * 16384>(o, vbi, pa0, pa1, pa2, pa3);
;     ...
;   if (PARTIAL) {
;     if (wid < 2) { float* po = PO + (wid * QBLK) * 128;
; #pragma unroll
;       for (int r = 0; r < 16; ++r) { const int orow = crow(r, hi);
; #pragma unroll
;         for (int d0 = 0; d0 < 4; ++d0) po[orow * 128 + d0 * 32 + r32] = o[d0][r]; }
;       if (hi == 0) { PO[8192 + (wid * QBLK + r32) * 2] = m_reg; PO[8192 + (wid * QBLK + r32) * 2 + 1] = l_reg; } }
;     __syncthreads();
;     return;
;   }
;   if (hi == 0) li_l[r32] = l_reg; asm volatile("s_waitcnt lgkmcnt(0)" ::: "memory");
	s_nop 0
	v_mfma_f32_32x32x16_bf16 v[0:15], v[72:75], v[94:97], v[0:15]
	ds_read_b64_tr_b16 v[94:95], v206 offset:0x4200
	ds_read_b64_tr_b16 v[96:97], v206 offset:0x4a00
	v_mfma_f32_32x32x16_bf16 v[0:15], v[76:79], v[98:101], v[0:15]
	ds_read_b64_tr_b16 v[98:99], v206 offset:0x5200
	ds_read_b64_tr_b16 v[100:101], v206 offset:0x5a00
	v_mfma_f32_32x32x16_bf16 v[0:15], v[80:83], v[102:105], v[0:15]
	ds_read_b64_tr_b16 v[102:103], v206 offset:0x6200
	ds_read_b64_tr_b16 v[104:105], v206 offset:0x6a00
	v_mfma_f32_32x32x16_bf16 v[0:15], v[90:93], v[106:109], v[0:15]
	ds_read_b64_tr_b16 v[106:107], v206 offset:0x7200
	ds_read_b64_tr_b16 v[108:109], v206 offset:0x7a00
	s_waitcnt lgkmcnt(0)
	v_mfma_f32_32x32x16_bf16 v[16:31], v[72:75], v[94:97], v[16:31]
	ds_read_b64_tr_b16 v[94:95], v206 offset:0x4400
	ds_read_b64_tr_b16 v[96:97], v206 offset:0x4c00
	v_mfma_f32_32x32x16_bf16 v[16:31], v[76:79], v[98:101], v[16:31]
	ds_read_b64_tr_b16 v[98:99], v206 offset:0x5400
	ds_read_b64_tr_b16 v[100:101], v206 offset:0x5c00
	v_mfma_f32_32x32x16_bf16 v[16:31], v[80:83], v[102:105], v[16:31]
	ds_read_b64_tr_b16 v[102:103], v206 offset:0x6400
	ds_read_b64_tr_b16 v[104:105], v206 offset:0x6c00
	v_mfma_f32_32x32x16_bf16 v[16:31], v[90:93], v[106:109], v[16:31]
	ds_read_b64_tr_b16 v[106:107], v206 offset:0x7400
	ds_read_b64_tr_b16 v[108:109], v206 offset:0x7c00
	s_waitcnt lgkmcnt(0)
	v_mfma_f32_32x32x16_bf16 v[32:47], v[72:75], v[94:97], v[32:47]
	ds_read_b64_tr_b16 v[94:95], v206 offset:0x4600
	ds_read_b64_tr_b16 v[96:97], v206 offset:0x4e00
	v_mfma_f32_32x32x16_bf16 v[32:47], v[76:79], v[98:101], v[32:47]
	ds_read_b64_tr_b16 v[98:99], v206 offset:0x5600
	ds_read_b64_tr_b16 v[100:101], v206 offset:0x5e00
	v_mfma_f32_32x32x16_bf16 v[32:47], v[80:83], v[102:105], v[32:47]
	ds_read_b64_tr_b16 v[102:103], v206 offset:0x6600
	ds_read_b64_tr_b16 v[104:105], v206 offset:0x6e00
	v_mfma_f32_32x32x16_bf16 v[32:47], v[90:93], v[106:109], v[32:47]
	ds_read_b64_tr_b16 v[106:107], v206 offset:0x7600
	ds_read_b64_tr_b16 v[108:109], v206 offset:0x7e00
	s_waitcnt lgkmcnt(0)
	v_mfma_f32_32x32x16_bf16 v[48:63], v[72:75], v[94:97], v[48:63]
	v_exp_f32_e32 v64, v64
	v_exp_f32_e32 v65, v65
	v_exp_f32_e32 v66, v66
	v_exp_f32_e32 v67, v67
	v_exp_f32_e32 v68, v68
	v_exp_f32_e32 v69, v69
	v_exp_f32_e32 v70, v70
	v_mfma_f32_32x32x16_bf16 v[48:63], v[76:79], v[98:101], v[48:63]
	v_exp_f32_e32 v71, v71
	v_mfma_f32_32x32x16_bf16 v[48:63], v[80:83], v[102:105], v[48:63]
	v_mfma_f32_32x32x16_bf16 v[48:63], v[90:93], v[106:109], v[48:63]
	v_add_f32_e32 v72, 0, v64
	v_add_f32_e32 v72, v65, v72
	v_add_f32_e32 v72, v66, v72
	v_add_f32_e32 v72, v67, v72
	v_add_f32_e32 v72, v68, v72
	v_add_f32_e32 v72, v69, v72
	v_add_f32_e32 v72, v70, v72
	v_add_f32_e32 v72, v71, v72
	v_add_f32_e32 v85, 0, v72
	v_mov_b32_e32 v87, v85
	s_nop 1
	v_permlane32_swap_b32_e32 v85, v87
	v_cvt_pk_bf16_f32 v64, v64, v65
	v_cvt_pk_bf16_f32 v65, v66, v67
	v_cvt_pk_bf16_f32 v66, v68, v69
	v_cvt_pk_bf16_f32 v67, v70, v71
	v_cvt_pk_bf16_f32 v68, v129, v129
	v_cvt_pk_bf16_f32 v69, v129, v129
	v_cvt_pk_bf16_f32 v70, v129, v129
	v_cvt_pk_bf16_f32 v71, v129, v129
	v_cvt_pk_bf16_f32 v72, v129, v129
	v_cvt_pk_bf16_f32 v73, v129, v129
	v_cvt_pk_bf16_f32 v74, v129, v129
	v_cvt_pk_bf16_f32 v75, v129, v129
	v_cvt_pk_bf16_f32 v76, v129, v129
	v_cvt_pk_bf16_f32 v77, v129, v129
	v_cvt_pk_bf16_f32 v78, v129, v129
	v_cvt_pk_bf16_f32 v79, v129, v129
	s_nop 0
	v_permlane32_swap_b32_e32 v64, v66
	v_permlane32_swap_b32_e32 v65, v67
	v_permlane32_swap_b32_e32 v68, v70
	v_permlane32_swap_b32_e32 v69, v71
	v_permlane32_swap_b32_e32 v72, v74
	v_permlane32_swap_b32_e32 v73, v75
	v_permlane32_swap_b32_e32 v76, v78
	v_permlane32_swap_b32_e32 v77, v79
	ds_read_b64_tr_b16 v[80:81], v206 offset:0x8000
	ds_read_b64_tr_b16 v[82:83], v206 offset:0x8800
	ds_read_b64_tr_b16 v[90:91], v206 offset:0x9000
	ds_read_b64_tr_b16 v[92:93], v206 offset:0x9800
	ds_read_b64_tr_b16 v[94:95], v206 offset:0xa000
	ds_read_b64_tr_b16 v[96:97], v206 offset:0xa800
	ds_read_b64_tr_b16 v[98:99], v206 offset:0xb000
	ds_read_b64_tr_b16 v[100:101], v206 offset:0xb800
	s_waitcnt lgkmcnt(0)
	s_nop 0
	v_mfma_f32_32x32x16_bf16 v[0:15], v[64:67], v[80:83], v[0:15]
	ds_read_b64_tr_b16 v[80:81], v206 offset:0x8200
	ds_read_b64_tr_b16 v[82:83], v206 offset:0x8a00
	v_mfma_f32_32x32x16_bf16 v[0:15], v[68:71], v[90:93], v[0:15]
	ds_read_b64_tr_b16 v[90:91], v206 offset:0x9200
	ds_read_b64_tr_b16 v[92:93], v206 offset:0x9a00
	v_mfma_f32_32x32x16_bf16 v[0:15], v[72:75], v[94:97], v[0:15]
	ds_read_b64_tr_b16 v[94:95], v206 offset:0xa200
	ds_read_b64_tr_b16 v[96:97], v206 offset:0xaa00
	v_mfma_f32_32x32x16_bf16 v[0:15], v[76:79], v[98:101], v[0:15]
	ds_read_b64_tr_b16 v[98:99], v206 offset:0xb200
	ds_read_b64_tr_b16 v[100:101], v206 offset:0xba00
	s_waitcnt lgkmcnt(0)
	v_mfma_f32_32x32x16_bf16 v[16:31], v[64:67], v[80:83], v[16:31]
	ds_read_b64_tr_b16 v[80:81], v206 offset:0x8400
	ds_read_b64_tr_b16 v[82:83], v206 offset:0x8c00
	v_mfma_f32_32x32x16_bf16 v[16:31], v[68:71], v[90:93], v[16:31]
	ds_read_b64_tr_b16 v[90:91], v206 offset:0x9400
	ds_read_b64_tr_b16 v[92:93], v206 offset:0x9c00
	v_mfma_f32_32x32x16_bf16 v[16:31], v[72:75], v[94:97], v[16:31]
	ds_read_b64_tr_b16 v[94:95], v206 offset:0xa400
	ds_read_b64_tr_b16 v[96:97], v206 offset:0xac00
	v_mfma_f32_32x32x16_bf16 v[16:31], v[76:79], v[98:101], v[16:31]
	ds_read_b64_tr_b16 v[98:99], v206 offset:0xb400
	ds_read_b64_tr_b16 v[100:101], v206 offset:0xbc00
	s_waitcnt lgkmcnt(0)
	v_mfma_f32_32x32x16_bf16 v[32:47], v[64:67], v[80:83], v[32:47]
	ds_read_b64_tr_b16 v[80:81], v206 offset:0x8600
	ds_read_b64_tr_b16 v[82:83], v206 offset:0x8e00
	v_mfma_f32_32x32x16_bf16 v[32:47], v[68:71], v[90:93], v[32:47]
	ds_read_b64_tr_b16 v[90:91], v206 offset:0x9600
	ds_read_b64_tr_b16 v[92:93], v206 offset:0x9e00
	v_mfma_f32_32x32x16_bf16 v[32:47], v[72:75], v[94:97], v[32:47]
	ds_read_b64_tr_b16 v[94:95], v206 offset:0xa600
	ds_read_b64_tr_b16 v[96:97], v206 offset:0xae00
	v_mfma_f32_32x32x16_bf16 v[32:47], v[76:79], v[98:101], v[32:47]
	ds_read_b64_tr_b16 v[98:99], v206 offset:0xb600
	ds_read_b64_tr_b16 v[100:101], v206 offset:0xbe00
	s_waitcnt lgkmcnt(0)
	v_mfma_f32_32x32x16_bf16 v[48:63], v[64:67], v[80:83], v[48:63]
	v_cmp_gt_u32_e32 vcc, 32, v190
	v_mfma_f32_32x32x16_bf16 v[48:63], v[68:71], v[90:93], v[48:63]
	v_mfma_f32_32x32x16_bf16 v[48:63], v[72:75], v[94:97], v[48:63]
	v_mfma_f32_32x32x16_bf16 v[48:63], v[76:79], v[98:101], v[48:63]
	s_and_saveexec_b64 s[28:29], vcc
	s_cbranch_execz .LBB0_309
	v_add_f32_e32 v64, v128, v218
	v_add_f32_e32 v66, v215, v64
	v_pk_add_f32 v[64:65], v[84:85], v[86:87]
	v_lshl_add_u32 v67, v192, 2, v88
	v_add_f32_e32 v64, v66, v64
	v_add_f32_e32 v64, v64, v65
	ds_write_b32 v67, v64
	s_branch .LBB0_309
